# conv LN butterfly with batched bpermutes; out-proj epilogue keeps gate in registers and prefetches final_g before the row-norm exchange
# speedup vs baseline: 1.0298x; 1.0024x over previous
.LBB0_377:
	s_or_b64 exec, exec, s[22:23]
	flat_load_dwordx2 v[200:201], v[70:71]
	flat_load_dwordx2 v[198:199], v[80:81]
	flat_load_dwordx2 v[196:197], v[82:83]
	flat_load_dwordx2 v[194:195], v[84:85]
	flat_load_dwordx2 v[192:193], v[86:87]
	flat_load_dwordx2 v[190:191], v[88:89]
	flat_load_dwordx2 v[188:189], v[90:91]
	flat_load_dwordx2 v[186:187], v[92:93]
	flat_load_dwordx2 v[184:185], v[94:95]
	flat_load_dwordx2 v[182:183], v[96:97]
	flat_load_dwordx2 v[180:181], v[98:99]
	flat_load_dwordx2 v[178:179], v[100:101]
	flat_load_dwordx2 v[176:177], v[102:103]
	flat_load_dwordx2 v[174:175], v[104:105]
	flat_load_dwordx2 v[172:173], v[106:107]
	flat_load_dwordx2 v[170:171], v[108:109]
	flat_load_dwordx2 v[168:169], v[110:111]
	flat_load_dwordx2 v[166:167], v[112:113]
	flat_load_dwordx2 v[164:165], v[114:115]
	flat_load_dwordx2 v[162:163], v[116:117]
	flat_load_dwordx2 v[160:161], v[118:119]
	flat_load_dwordx2 v[158:159], v[120:121]
	flat_load_dwordx2 v[156:157], v[122:123]
	flat_load_dwordx2 v[154:155], v[124:125]
	flat_load_dwordx2 v[152:153], v[126:127]
	flat_load_dwordx2 v[150:151], v[128:129]
	flat_load_dwordx2 v[148:149], v[130:131]
	flat_load_dwordx2 v[146:147], v[132:133]
	flat_load_dwordx2 v[144:145], v[134:135]
	flat_load_dwordx2 v[142:143], v[136:137]
	flat_load_dwordx2 v[140:141], v[138:139]
	s_waitcnt vmcnt(0) lgkmcnt(0)
	ds_write_b128 v223, v[2:5]
	ds_write_b128 v223, v[10:13] offset:8192
	ds_write_b128 v223, v[6:9] offset:16384
	ds_write_b128 v223, v[18:21] offset:24576
	ds_write_b128 v223, v[14:17] offset:32768
	ds_write_b128 v223, v[26:29] offset:40960
	ds_write_b128 v223, v[22:25] offset:49152
	ds_write_b128 v223, v[34:37] offset:57344
	ds_write_b128 v224, v[30:33]
	ds_write_b128 v225, v[42:45]
	ds_write_b128 v226, v[38:41]
	ds_write_b128 v227, v[50:53]
	ds_write_b128 v228, v[46:49]
	ds_write_b128 v229, v[58:61]
	s_and_saveexec_b64 s[22:23], s[16:17]
	ds_write_b128 v230, v[54:57]
	s_or_b64 exec, exec, s[22:23]
	s_and_saveexec_b64 s[22:23], s[18:19]
	v_add_u32_e32 v2, 0x1e000, v223
	ds_write_b128 v2, v[62:65]
	s_or_b64 exec, exec, s[22:23]
	s_waitcnt lgkmcnt(0)
	s_barrier
	flat_load_dwordx2 v[2:3], v[72:73]
	ds_read2st64_b32 v[4:5], v202 offset1:8
	ds_read2st64_b32 v[8:9], v202 offset0:16 offset1:24
	ds_read2st64_b32 v[12:13], v202 offset0:32 offset1:40
	ds_read2st64_b32 v[16:17], v202 offset0:48 offset1:56
	s_waitcnt lgkmcnt(0)
	v_lshlrev_b32_e32 v6, 16, v4
	v_and_b32_e32 v7, 0xffff0000, v4
	v_lshlrev_b32_e32 v4, 16, v5
	v_and_b32_e32 v5, 0xffff0000, v5
	v_lshlrev_b32_e32 v10, 16, v8
	v_and_b32_e32 v11, 0xffff0000, v8
	v_lshlrev_b32_e32 v8, 16, v9
	v_and_b32_e32 v9, 0xffff0000, v9
	ds_read2st64_b32 v[20:21], v202 offset0:64 offset1:72
	v_lshlrev_b32_e32 v14, 16, v12
	v_and_b32_e32 v15, 0xffff0000, v12
	v_lshlrev_b32_e32 v12, 16, v13
	v_and_b32_e32 v13, 0xffff0000, v13
	v_lshlrev_b32_e32 v18, 16, v16
	v_and_b32_e32 v19, 0xffff0000, v16
	v_lshlrev_b32_e32 v16, 16, v17
	v_and_b32_e32 v17, 0xffff0000, v17
	s_waitcnt lgkmcnt(0)
	v_lshlrev_b32_e32 v22, 16, v20
	v_and_b32_e32 v23, 0xffff0000, v20
	v_lshlrev_b32_e32 v20, 16, v21
	v_and_b32_e32 v21, 0xffff0000, v21
	ds_read2st64_b32 v[32:33], v202 offset0:112 offset1:120
	s_waitcnt lgkmcnt(0)
	v_lshlrev_b32_e32 v34, 16, v32
	v_and_b32_e32 v35, 0xffff0000, v32
	v_lshlrev_b32_e32 v32, 16, v33
	v_and_b32_e32 v33, 0xffff0000, v33
	s_waitcnt vmcnt(0)
	v_pk_fma_f32 v[6:7], v[200:201], v[6:7], v[2:3]
	s_nop 0
	v_pk_fma_f32 v[6:7], v[198:199], v[4:5], v[6:7]
	v_pk_fma_f32 v[4:5], v[200:201], v[4:5], v[2:3]
	v_pk_fma_f32 v[6:7], v[196:197], v[10:11], v[6:7]
	v_pk_fma_f32 v[4:5], v[198:199], v[10:11], v[4:5]
	v_pk_fma_f32 v[10:11], v[200:201], v[10:11], v[2:3]
	v_pk_fma_f32 v[6:7], v[194:195], v[8:9], v[6:7]
	v_pk_fma_f32 v[4:5], v[196:197], v[8:9], v[4:5]
	v_pk_fma_f32 v[10:11], v[198:199], v[8:9], v[10:11]
	v_pk_fma_f32 v[8:9], v[200:201], v[8:9], v[2:3]
	v_pk_fma_f32 v[6:7], v[192:193], v[14:15], v[6:7]
	v_pk_fma_f32 v[4:5], v[194:195], v[14:15], v[4:5]
	v_pk_fma_f32 v[10:11], v[196:197], v[14:15], v[10:11]
	v_pk_fma_f32 v[8:9], v[198:199], v[14:15], v[8:9]
	v_pk_fma_f32 v[14:15], v[200:201], v[14:15], v[2:3]
	v_pk_fma_f32 v[6:7], v[190:191], v[12:13], v[6:7]
	v_pk_fma_f32 v[4:5], v[192:193], v[12:13], v[4:5]
	v_pk_fma_f32 v[10:11], v[194:195], v[12:13], v[10:11]
	v_pk_fma_f32 v[8:9], v[196:197], v[12:13], v[8:9]
	v_pk_fma_f32 v[14:15], v[198:199], v[12:13], v[14:15]
	v_pk_fma_f32 v[12:13], v[200:201], v[12:13], v[2:3]
	v_pk_fma_f32 v[6:7], v[188:189], v[18:19], v[6:7]
	v_pk_fma_f32 v[4:5], v[190:191], v[18:19], v[4:5]
	v_pk_fma_f32 v[10:11], v[192:193], v[18:19], v[10:11]
	v_pk_fma_f32 v[8:9], v[194:195], v[18:19], v[8:9]
	v_pk_fma_f32 v[14:15], v[196:197], v[18:19], v[14:15]
	v_pk_fma_f32 v[12:13], v[198:199], v[18:19], v[12:13]
	v_pk_fma_f32 v[18:19], v[200:201], v[18:19], v[2:3]
	v_pk_fma_f32 v[6:7], v[186:187], v[16:17], v[6:7]
	v_pk_fma_f32 v[4:5], v[188:189], v[16:17], v[4:5]
	v_pk_fma_f32 v[10:11], v[190:191], v[16:17], v[10:11]
	v_pk_fma_f32 v[8:9], v[192:193], v[16:17], v[8:9]
	v_pk_fma_f32 v[14:15], v[194:195], v[16:17], v[14:15]
	v_pk_fma_f32 v[12:13], v[196:197], v[16:17], v[12:13]
	v_pk_fma_f32 v[18:19], v[198:199], v[16:17], v[18:19]
	v_pk_fma_f32 v[16:17], v[200:201], v[16:17], v[2:3]
	v_pk_fma_f32 v[6:7], v[184:185], v[22:23], v[6:7]
	v_pk_fma_f32 v[4:5], v[186:187], v[22:23], v[4:5]
	v_pk_fma_f32 v[10:11], v[188:189], v[22:23], v[10:11]
	v_pk_fma_f32 v[8:9], v[190:191], v[22:23], v[8:9]
	v_pk_fma_f32 v[14:15], v[192:193], v[22:23], v[14:15]
	v_pk_fma_f32 v[12:13], v[194:195], v[22:23], v[12:13]
	v_pk_fma_f32 v[24:25], v[196:197], v[22:23], v[18:19]
	v_pk_fma_f32 v[16:17], v[198:199], v[22:23], v[16:17]
	v_pk_fma_f32 v[22:23], v[200:201], v[22:23], v[2:3]
	v_pk_fma_f32 v[26:27], v[182:183], v[20:21], v[6:7]
	v_pk_fma_f32 v[28:29], v[184:185], v[20:21], v[4:5]
	v_pk_fma_f32 v[18:19], v[186:187], v[20:21], v[10:11]
	v_pk_fma_f32 v[4:5], v[188:189], v[20:21], v[8:9]
	v_pk_fma_f32 v[6:7], v[190:191], v[20:21], v[14:15]
	v_pk_fma_f32 v[8:9], v[192:193], v[20:21], v[12:13]
	v_pk_fma_f32 v[10:11], v[194:195], v[20:21], v[24:25]
	v_pk_fma_f32 v[12:13], v[196:197], v[20:21], v[16:17]
	v_pk_fma_f32 v[14:15], v[198:199], v[20:21], v[22:23]
	v_pk_fma_f32 v[16:17], v[200:201], v[20:21], v[2:3]
	ds_read2st64_b32 v[20:21], v202 offset0:80 offset1:88
	s_waitcnt lgkmcnt(0)
	v_lshlrev_b32_e32 v22, 16, v20
	v_and_b32_e32 v23, 0xffff0000, v20
	v_pk_fma_f32 v[24:25], v[180:181], v[22:23], v[26:27]
	v_pk_fma_f32 v[26:27], v[182:183], v[22:23], v[28:29]
	ds_read2st64_b32 v[28:29], v202 offset0:96 offset1:104
	v_pk_fma_f32 v[18:19], v[184:185], v[22:23], v[18:19]
	v_pk_fma_f32 v[4:5], v[186:187], v[22:23], v[4:5]
	v_pk_fma_f32 v[6:7], v[188:189], v[22:23], v[6:7]
	v_pk_fma_f32 v[8:9], v[190:191], v[22:23], v[8:9]
	v_pk_fma_f32 v[10:11], v[192:193], v[22:23], v[10:11]
	v_pk_fma_f32 v[12:13], v[194:195], v[22:23], v[12:13]
	v_pk_fma_f32 v[14:15], v[196:197], v[22:23], v[14:15]
	v_pk_fma_f32 v[16:17], v[198:199], v[22:23], v[16:17]
	v_pk_fma_f32 v[22:23], v[200:201], v[22:23], v[2:3]
	v_lshlrev_b32_e32 v20, 16, v21
	v_and_b32_e32 v21, 0xffff0000, v21
	ds_read2st64_b32 v[36:37], v202 offset0:128 offset1:136
	v_pk_fma_f32 v[24:25], v[178:179], v[20:21], v[24:25]
	v_pk_fma_f32 v[26:27], v[180:181], v[20:21], v[26:27]
	v_pk_fma_f32 v[18:19], v[182:183], v[20:21], v[18:19]
	v_pk_fma_f32 v[4:5], v[184:185], v[20:21], v[4:5]
	v_pk_fma_f32 v[6:7], v[186:187], v[20:21], v[6:7]
	v_pk_fma_f32 v[8:9], v[188:189], v[20:21], v[8:9]
	v_pk_fma_f32 v[10:11], v[190:191], v[20:21], v[10:11]
	v_pk_fma_f32 v[12:13], v[192:193], v[20:21], v[12:13]
	v_pk_fma_f32 v[14:15], v[194:195], v[20:21], v[14:15]
	v_pk_fma_f32 v[16:17], v[196:197], v[20:21], v[16:17]
	v_pk_fma_f32 v[22:23], v[198:199], v[20:21], v[22:23]
	v_pk_fma_f32 v[20:21], v[200:201], v[20:21], v[2:3]
	s_waitcnt lgkmcnt(1)
	v_lshlrev_b32_e32 v30, 16, v28
	v_and_b32_e32 v31, 0xffff0000, v28
	v_pk_fma_f32 v[24:25], v[176:177], v[30:31], v[24:25]
	v_pk_fma_f32 v[26:27], v[178:179], v[30:31], v[26:27]
	v_pk_fma_f32 v[18:19], v[180:181], v[30:31], v[18:19]
	v_pk_fma_f32 v[4:5], v[182:183], v[30:31], v[4:5]
	v_pk_fma_f32 v[6:7], v[184:185], v[30:31], v[6:7]
	v_pk_fma_f32 v[8:9], v[186:187], v[30:31], v[8:9]
	v_pk_fma_f32 v[10:11], v[188:189], v[30:31], v[10:11]
	v_pk_fma_f32 v[12:13], v[190:191], v[30:31], v[12:13]
	v_pk_fma_f32 v[14:15], v[192:193], v[30:31], v[14:15]
	v_pk_fma_f32 v[16:17], v[194:195], v[30:31], v[16:17]
	v_pk_fma_f32 v[22:23], v[196:197], v[30:31], v[22:23]
	v_pk_fma_f32 v[20:21], v[198:199], v[30:31], v[20:21]
	v_pk_fma_f32 v[30:31], v[200:201], v[30:31], v[2:3]
	v_lshlrev_b32_e32 v28, 16, v29
	v_and_b32_e32 v29, 0xffff0000, v29
	ds_read2st64_b32 v[40:41], v202 offset0:144 offset1:152
	v_pk_fma_f32 v[24:25], v[174:175], v[28:29], v[24:25]
	v_pk_fma_f32 v[26:27], v[176:177], v[28:29], v[26:27]
	v_pk_fma_f32 v[18:19], v[178:179], v[28:29], v[18:19]
	v_pk_fma_f32 v[4:5], v[180:181], v[28:29], v[4:5]
	v_pk_fma_f32 v[6:7], v[182:183], v[28:29], v[6:7]
	v_pk_fma_f32 v[8:9], v[184:185], v[28:29], v[8:9]
	v_pk_fma_f32 v[10:11], v[186:187], v[28:29], v[10:11]
	v_pk_fma_f32 v[12:13], v[188:189], v[28:29], v[12:13]
	v_pk_fma_f32 v[14:15], v[190:191], v[28:29], v[14:15]
	v_pk_fma_f32 v[16:17], v[192:193], v[28:29], v[16:17]
	v_pk_fma_f32 v[22:23], v[194:195], v[28:29], v[22:23]
	v_pk_fma_f32 v[20:21], v[196:197], v[28:29], v[20:21]
	v_pk_fma_f32 v[30:31], v[198:199], v[28:29], v[30:31]
	v_pk_fma_f32 v[28:29], v[200:201], v[28:29], v[2:3]
	v_pk_fma_f32 v[24:25], v[172:173], v[34:35], v[24:25]
	v_pk_fma_f32 v[26:27], v[174:175], v[34:35], v[26:27]
	v_pk_fma_f32 v[18:19], v[176:177], v[34:35], v[18:19]
	v_pk_fma_f32 v[4:5], v[178:179], v[34:35], v[4:5]
	v_pk_fma_f32 v[6:7], v[180:181], v[34:35], v[6:7]
	v_pk_fma_f32 v[8:9], v[182:183], v[34:35], v[8:9]
	v_pk_fma_f32 v[10:11], v[184:185], v[34:35], v[10:11]
	v_pk_fma_f32 v[12:13], v[186:187], v[34:35], v[12:13]
	v_pk_fma_f32 v[14:15], v[188:189], v[34:35], v[14:15]
	v_pk_fma_f32 v[16:17], v[190:191], v[34:35], v[16:17]
	v_pk_fma_f32 v[22:23], v[192:193], v[34:35], v[22:23]
	v_pk_fma_f32 v[20:21], v[194:195], v[34:35], v[20:21]
	v_pk_fma_f32 v[30:31], v[196:197], v[34:35], v[30:31]
	v_pk_fma_f32 v[28:29], v[198:199], v[34:35], v[28:29]
	v_pk_fma_f32 v[34:35], v[200:201], v[34:35], v[2:3]
	ds_read2st64_b32 v[44:45], v202 offset0:160 offset1:168
	v_pk_fma_f32 v[24:25], v[170:171], v[32:33], v[24:25]
	v_pk_fma_f32 v[26:27], v[172:173], v[32:33], v[26:27]
	v_pk_fma_f32 v[18:19], v[174:175], v[32:33], v[18:19]
	v_pk_fma_f32 v[4:5], v[176:177], v[32:33], v[4:5]
	v_pk_fma_f32 v[6:7], v[178:179], v[32:33], v[6:7]
	v_pk_fma_f32 v[8:9], v[180:181], v[32:33], v[8:9]
	v_pk_fma_f32 v[10:11], v[182:183], v[32:33], v[10:11]
	v_pk_fma_f32 v[12:13], v[184:185], v[32:33], v[12:13]
	v_pk_fma_f32 v[14:15], v[186:187], v[32:33], v[14:15]
	v_pk_fma_f32 v[16:17], v[188:189], v[32:33], v[16:17]
	v_pk_fma_f32 v[22:23], v[190:191], v[32:33], v[22:23]
	v_pk_fma_f32 v[20:21], v[192:193], v[32:33], v[20:21]
	v_pk_fma_f32 v[30:31], v[194:195], v[32:33], v[30:31]
	v_pk_fma_f32 v[28:29], v[196:197], v[32:33], v[28:29]
	v_pk_fma_f32 v[34:35], v[198:199], v[32:33], v[34:35]
	v_pk_fma_f32 v[32:33], v[200:201], v[32:33], v[2:3]
	s_waitcnt lgkmcnt(2)
	v_lshlrev_b32_e32 v38, 16, v36
	v_and_b32_e32 v39, 0xffff0000, v36
	v_pk_fma_f32 v[24:25], v[168:169], v[38:39], v[24:25]
	v_pk_fma_f32 v[26:27], v[170:171], v[38:39], v[26:27]
	v_pk_fma_f32 v[18:19], v[172:173], v[38:39], v[18:19]
	v_pk_fma_f32 v[4:5], v[174:175], v[38:39], v[4:5]
	v_pk_fma_f32 v[6:7], v[176:177], v[38:39], v[6:7]
	v_pk_fma_f32 v[8:9], v[178:179], v[38:39], v[8:9]
	v_pk_fma_f32 v[10:11], v[180:181], v[38:39], v[10:11]
	v_pk_fma_f32 v[12:13], v[182:183], v[38:39], v[12:13]
	v_pk_fma_f32 v[14:15], v[184:185], v[38:39], v[14:15]
	v_pk_fma_f32 v[16:17], v[186:187], v[38:39], v[16:17]
	v_pk_fma_f32 v[22:23], v[188:189], v[38:39], v[22:23]
	v_pk_fma_f32 v[20:21], v[190:191], v[38:39], v[20:21]
	v_pk_fma_f32 v[30:31], v[192:193], v[38:39], v[30:31]
	v_pk_fma_f32 v[28:29], v[194:195], v[38:39], v[28:29]
	v_pk_fma_f32 v[34:35], v[196:197], v[38:39], v[34:35]
	v_pk_fma_f32 v[32:33], v[198:199], v[38:39], v[32:33]
	v_pk_fma_f32 v[38:39], v[200:201], v[38:39], v[2:3]
	v_lshlrev_b32_e32 v36, 16, v37
	v_and_b32_e32 v37, 0xffff0000, v37
	ds_read2st64_b32 v[48:49], v202 offset0:176 offset1:184
	v_pk_fma_f32 v[24:25], v[166:167], v[36:37], v[24:25]
	v_pk_fma_f32 v[26:27], v[168:169], v[36:37], v[26:27]
	v_pk_fma_f32 v[18:19], v[170:171], v[36:37], v[18:19]
	v_pk_fma_f32 v[4:5], v[172:173], v[36:37], v[4:5]
	v_pk_fma_f32 v[6:7], v[174:175], v[36:37], v[6:7]
	v_pk_fma_f32 v[8:9], v[176:177], v[36:37], v[8:9]
	v_pk_fma_f32 v[10:11], v[178:179], v[36:37], v[10:11]
	v_pk_fma_f32 v[12:13], v[180:181], v[36:37], v[12:13]
	v_pk_fma_f32 v[14:15], v[182:183], v[36:37], v[14:15]
	v_pk_fma_f32 v[16:17], v[184:185], v[36:37], v[16:17]
	v_pk_fma_f32 v[22:23], v[186:187], v[36:37], v[22:23]
	v_pk_fma_f32 v[20:21], v[188:189], v[36:37], v[20:21]
	v_pk_fma_f32 v[30:31], v[190:191], v[36:37], v[30:31]
	v_pk_fma_f32 v[28:29], v[192:193], v[36:37], v[28:29]
	v_pk_fma_f32 v[34:35], v[194:195], v[36:37], v[34:35]
	v_pk_fma_f32 v[32:33], v[196:197], v[36:37], v[32:33]
	v_pk_fma_f32 v[38:39], v[198:199], v[36:37], v[38:39]
	v_pk_fma_f32 v[36:37], v[200:201], v[36:37], v[2:3]
	s_waitcnt lgkmcnt(2)
	v_lshlrev_b32_e32 v42, 16, v40
	v_and_b32_e32 v43, 0xffff0000, v40
	v_pk_fma_f32 v[24:25], v[164:165], v[42:43], v[24:25]
	v_pk_fma_f32 v[26:27], v[166:167], v[42:43], v[26:27]
	v_pk_fma_f32 v[18:19], v[168:169], v[42:43], v[18:19]
	v_pk_fma_f32 v[4:5], v[170:171], v[42:43], v[4:5]
	v_pk_fma_f32 v[6:7], v[172:173], v[42:43], v[6:7]
	v_pk_fma_f32 v[8:9], v[174:175], v[42:43], v[8:9]
	v_pk_fma_f32 v[10:11], v[176:177], v[42:43], v[10:11]
	v_pk_fma_f32 v[12:13], v[178:179], v[42:43], v[12:13]
	v_pk_fma_f32 v[14:15], v[180:181], v[42:43], v[14:15]
	v_pk_fma_f32 v[16:17], v[182:183], v[42:43], v[16:17]
	v_pk_fma_f32 v[22:23], v[184:185], v[42:43], v[22:23]
	v_pk_fma_f32 v[20:21], v[186:187], v[42:43], v[20:21]
	v_pk_fma_f32 v[30:31], v[188:189], v[42:43], v[30:31]
	v_pk_fma_f32 v[28:29], v[190:191], v[42:43], v[28:29]
	v_pk_fma_f32 v[34:35], v[192:193], v[42:43], v[34:35]
	v_pk_fma_f32 v[32:33], v[194:195], v[42:43], v[32:33]
	v_pk_fma_f32 v[38:39], v[196:197], v[42:43], v[38:39]
	v_pk_fma_f32 v[36:37], v[198:199], v[42:43], v[36:37]
	v_pk_fma_f32 v[42:43], v[200:201], v[42:43], v[2:3]
	v_lshlrev_b32_e32 v40, 16, v41
	v_and_b32_e32 v41, 0xffff0000, v41
	ds_read2st64_b32 v[52:53], v202 offset0:192 offset1:200
	v_pk_fma_f32 v[24:25], v[162:163], v[40:41], v[24:25]
	v_pk_fma_f32 v[26:27], v[164:165], v[40:41], v[26:27]
	v_pk_fma_f32 v[18:19], v[166:167], v[40:41], v[18:19]
	v_pk_fma_f32 v[4:5], v[168:169], v[40:41], v[4:5]
	v_pk_fma_f32 v[6:7], v[170:171], v[40:41], v[6:7]
	v_pk_fma_f32 v[8:9], v[172:173], v[40:41], v[8:9]
	v_pk_fma_f32 v[10:11], v[174:175], v[40:41], v[10:11]
	v_pk_fma_f32 v[12:13], v[176:177], v[40:41], v[12:13]
	v_pk_fma_f32 v[14:15], v[178:179], v[40:41], v[14:15]
	v_pk_fma_f32 v[16:17], v[180:181], v[40:41], v[16:17]
	v_pk_fma_f32 v[22:23], v[182:183], v[40:41], v[22:23]
	v_pk_fma_f32 v[20:21], v[184:185], v[40:41], v[20:21]
	v_pk_fma_f32 v[30:31], v[186:187], v[40:41], v[30:31]
	v_pk_fma_f32 v[28:29], v[188:189], v[40:41], v[28:29]
	v_pk_fma_f32 v[34:35], v[190:191], v[40:41], v[34:35]
	v_pk_fma_f32 v[32:33], v[192:193], v[40:41], v[32:33]
	v_pk_fma_f32 v[38:39], v[194:195], v[40:41], v[38:39]
	v_pk_fma_f32 v[36:37], v[196:197], v[40:41], v[36:37]
	v_pk_fma_f32 v[42:43], v[198:199], v[40:41], v[42:43]
	v_pk_fma_f32 v[40:41], v[200:201], v[40:41], v[2:3]
	s_waitcnt lgkmcnt(2)
	v_lshlrev_b32_e32 v46, 16, v44
	v_and_b32_e32 v47, 0xffff0000, v44
	v_pk_fma_f32 v[24:25], v[160:161], v[46:47], v[24:25]
	v_pk_fma_f32 v[26:27], v[162:163], v[46:47], v[26:27]
	v_pk_fma_f32 v[18:19], v[164:165], v[46:47], v[18:19]
	v_pk_fma_f32 v[4:5], v[166:167], v[46:47], v[4:5]
	v_pk_fma_f32 v[6:7], v[168:169], v[46:47], v[6:7]
	v_pk_fma_f32 v[8:9], v[170:171], v[46:47], v[8:9]
	v_pk_fma_f32 v[10:11], v[172:173], v[46:47], v[10:11]
	v_pk_fma_f32 v[12:13], v[174:175], v[46:47], v[12:13]
	v_pk_fma_f32 v[14:15], v[176:177], v[46:47], v[14:15]
	v_pk_fma_f32 v[16:17], v[178:179], v[46:47], v[16:17]
	v_pk_fma_f32 v[22:23], v[180:181], v[46:47], v[22:23]
	v_pk_fma_f32 v[20:21], v[182:183], v[46:47], v[20:21]
	v_pk_fma_f32 v[30:31], v[184:185], v[46:47], v[30:31]
	v_pk_fma_f32 v[28:29], v[186:187], v[46:47], v[28:29]
	v_pk_fma_f32 v[34:35], v[188:189], v[46:47], v[34:35]
	v_pk_fma_f32 v[32:33], v[190:191], v[46:47], v[32:33]
	v_pk_fma_f32 v[38:39], v[192:193], v[46:47], v[38:39]
	v_pk_fma_f32 v[36:37], v[194:195], v[46:47], v[36:37]
	v_pk_fma_f32 v[42:43], v[196:197], v[46:47], v[42:43]
	v_pk_fma_f32 v[40:41], v[198:199], v[46:47], v[40:41]
	v_pk_fma_f32 v[46:47], v[200:201], v[46:47], v[2:3]
	v_lshlrev_b32_e32 v44, 16, v45
	v_and_b32_e32 v45, 0xffff0000, v45
	ds_read2st64_b32 v[56:57], v202 offset0:208 offset1:216
	v_pk_fma_f32 v[24:25], v[158:159], v[44:45], v[24:25]
	v_pk_fma_f32 v[26:27], v[160:161], v[44:45], v[26:27]
	v_pk_fma_f32 v[18:19], v[162:163], v[44:45], v[18:19]
	v_pk_fma_f32 v[4:5], v[164:165], v[44:45], v[4:5]
	v_pk_fma_f32 v[6:7], v[166:167], v[44:45], v[6:7]
	v_pk_fma_f32 v[8:9], v[168:169], v[44:45], v[8:9]
	v_pk_fma_f32 v[10:11], v[170:171], v[44:45], v[10:11]
	v_pk_fma_f32 v[12:13], v[172:173], v[44:45], v[12:13]
	v_pk_fma_f32 v[14:15], v[174:175], v[44:45], v[14:15]
	v_pk_fma_f32 v[16:17], v[176:177], v[44:45], v[16:17]
	v_pk_fma_f32 v[22:23], v[178:179], v[44:45], v[22:23]
	v_pk_fma_f32 v[20:21], v[180:181], v[44:45], v[20:21]
	v_pk_fma_f32 v[30:31], v[182:183], v[44:45], v[30:31]
	v_pk_fma_f32 v[28:29], v[184:185], v[44:45], v[28:29]
	v_pk_fma_f32 v[34:35], v[186:187], v[44:45], v[34:35]
	v_pk_fma_f32 v[32:33], v[188:189], v[44:45], v[32:33]
	v_pk_fma_f32 v[38:39], v[190:191], v[44:45], v[38:39]
	v_pk_fma_f32 v[36:37], v[192:193], v[44:45], v[36:37]
	v_pk_fma_f32 v[42:43], v[194:195], v[44:45], v[42:43]
	v_pk_fma_f32 v[40:41], v[196:197], v[44:45], v[40:41]
	v_pk_fma_f32 v[46:47], v[198:199], v[44:45], v[46:47]
	v_pk_fma_f32 v[44:45], v[200:201], v[44:45], v[2:3]
	s_waitcnt lgkmcnt(2)
	v_lshlrev_b32_e32 v50, 16, v48
	v_and_b32_e32 v51, 0xffff0000, v48
	v_pk_fma_f32 v[24:25], v[156:157], v[50:51], v[24:25]
	v_pk_fma_f32 v[26:27], v[158:159], v[50:51], v[26:27]
	v_pk_fma_f32 v[18:19], v[160:161], v[50:51], v[18:19]
	v_pk_fma_f32 v[4:5], v[162:163], v[50:51], v[4:5]
	v_pk_fma_f32 v[6:7], v[164:165], v[50:51], v[6:7]
	v_pk_fma_f32 v[8:9], v[166:167], v[50:51], v[8:9]
	v_pk_fma_f32 v[10:11], v[168:169], v[50:51], v[10:11]
	v_pk_fma_f32 v[12:13], v[170:171], v[50:51], v[12:13]
	v_pk_fma_f32 v[14:15], v[172:173], v[50:51], v[14:15]
	v_pk_fma_f32 v[16:17], v[174:175], v[50:51], v[16:17]
	v_pk_fma_f32 v[22:23], v[176:177], v[50:51], v[22:23]
	v_pk_fma_f32 v[20:21], v[178:179], v[50:51], v[20:21]
	v_pk_fma_f32 v[30:31], v[180:181], v[50:51], v[30:31]
	v_pk_fma_f32 v[28:29], v[182:183], v[50:51], v[28:29]
	v_pk_fma_f32 v[34:35], v[184:185], v[50:51], v[34:35]
	v_pk_fma_f32 v[32:33], v[186:187], v[50:51], v[32:33]
	v_pk_fma_f32 v[38:39], v[188:189], v[50:51], v[38:39]
	v_pk_fma_f32 v[36:37], v[190:191], v[50:51], v[36:37]
	v_pk_fma_f32 v[42:43], v[192:193], v[50:51], v[42:43]
	v_pk_fma_f32 v[40:41], v[194:195], v[50:51], v[40:41]
	v_pk_fma_f32 v[46:47], v[196:197], v[50:51], v[46:47]
	v_pk_fma_f32 v[44:45], v[198:199], v[50:51], v[44:45]
	v_pk_fma_f32 v[50:51], v[200:201], v[50:51], v[2:3]
	v_lshlrev_b32_e32 v48, 16, v49
	v_and_b32_e32 v49, 0xffff0000, v49
	ds_read2st64_b32 v[60:61], v202 offset0:224 offset1:232
	v_pk_fma_f32 v[24:25], v[154:155], v[48:49], v[24:25]
	v_pk_fma_f32 v[26:27], v[156:157], v[48:49], v[26:27]
	v_pk_fma_f32 v[18:19], v[158:159], v[48:49], v[18:19]
	v_pk_fma_f32 v[4:5], v[160:161], v[48:49], v[4:5]
	v_pk_fma_f32 v[6:7], v[162:163], v[48:49], v[6:7]
	v_pk_fma_f32 v[8:9], v[164:165], v[48:49], v[8:9]
	v_pk_fma_f32 v[10:11], v[166:167], v[48:49], v[10:11]
	v_pk_fma_f32 v[12:13], v[168:169], v[48:49], v[12:13]
	v_pk_fma_f32 v[14:15], v[170:171], v[48:49], v[14:15]
	v_pk_fma_f32 v[16:17], v[172:173], v[48:49], v[16:17]
	v_pk_fma_f32 v[22:23], v[174:175], v[48:49], v[22:23]
	v_pk_fma_f32 v[20:21], v[176:177], v[48:49], v[20:21]
	v_pk_fma_f32 v[30:31], v[178:179], v[48:49], v[30:31]
	v_pk_fma_f32 v[28:29], v[180:181], v[48:49], v[28:29]
	v_pk_fma_f32 v[34:35], v[182:183], v[48:49], v[34:35]
	v_pk_fma_f32 v[32:33], v[184:185], v[48:49], v[32:33]
	v_pk_fma_f32 v[38:39], v[186:187], v[48:49], v[38:39]
	v_pk_fma_f32 v[36:37], v[188:189], v[48:49], v[36:37]
	v_pk_fma_f32 v[42:43], v[190:191], v[48:49], v[42:43]
	v_pk_fma_f32 v[40:41], v[192:193], v[48:49], v[40:41]
	v_pk_fma_f32 v[46:47], v[194:195], v[48:49], v[46:47]
	v_pk_fma_f32 v[44:45], v[196:197], v[48:49], v[44:45]
	v_pk_fma_f32 v[50:51], v[198:199], v[48:49], v[50:51]
	v_pk_fma_f32 v[48:49], v[200:201], v[48:49], v[2:3]
	s_waitcnt lgkmcnt(2)
	v_lshlrev_b32_e32 v54, 16, v52
	v_and_b32_e32 v55, 0xffff0000, v52
	v_pk_fma_f32 v[24:25], v[152:153], v[54:55], v[24:25]
	v_pk_fma_f32 v[26:27], v[154:155], v[54:55], v[26:27]
	v_pk_fma_f32 v[18:19], v[156:157], v[54:55], v[18:19]
	v_pk_fma_f32 v[4:5], v[158:159], v[54:55], v[4:5]
	v_pk_fma_f32 v[6:7], v[160:161], v[54:55], v[6:7]
	v_pk_fma_f32 v[8:9], v[162:163], v[54:55], v[8:9]
	v_pk_fma_f32 v[10:11], v[164:165], v[54:55], v[10:11]
	v_pk_fma_f32 v[12:13], v[166:167], v[54:55], v[12:13]
	v_pk_fma_f32 v[14:15], v[168:169], v[54:55], v[14:15]
	v_pk_fma_f32 v[16:17], v[170:171], v[54:55], v[16:17]
	v_pk_fma_f32 v[22:23], v[172:173], v[54:55], v[22:23]
	v_pk_fma_f32 v[20:21], v[174:175], v[54:55], v[20:21]
	v_pk_fma_f32 v[30:31], v[176:177], v[54:55], v[30:31]
	v_pk_fma_f32 v[28:29], v[178:179], v[54:55], v[28:29]
	v_pk_fma_f32 v[34:35], v[180:181], v[54:55], v[34:35]
	v_pk_fma_f32 v[32:33], v[182:183], v[54:55], v[32:33]
	v_pk_fma_f32 v[38:39], v[184:185], v[54:55], v[38:39]
	v_pk_fma_f32 v[36:37], v[186:187], v[54:55], v[36:37]
	v_pk_fma_f32 v[42:43], v[188:189], v[54:55], v[42:43]
	v_pk_fma_f32 v[40:41], v[190:191], v[54:55], v[40:41]
	v_pk_fma_f32 v[46:47], v[192:193], v[54:55], v[46:47]
	v_pk_fma_f32 v[44:45], v[194:195], v[54:55], v[44:45]
	v_pk_fma_f32 v[50:51], v[196:197], v[54:55], v[50:51]
	v_pk_fma_f32 v[48:49], v[198:199], v[54:55], v[48:49]
	v_pk_fma_f32 v[54:55], v[200:201], v[54:55], v[2:3]
	v_lshlrev_b32_e32 v52, 16, v53
	v_and_b32_e32 v53, 0xffff0000, v53
	ds_read2st64_b32 v[250:251], v202 offset0:240 offset1:248
	v_pk_fma_f32 v[24:25], v[150:151], v[52:53], v[24:25]
	v_pk_fma_f32 v[26:27], v[152:153], v[52:53], v[26:27]
	v_pk_fma_f32 v[18:19], v[154:155], v[52:53], v[18:19]
	v_pk_fma_f32 v[4:5], v[156:157], v[52:53], v[4:5]
	v_pk_fma_f32 v[6:7], v[158:159], v[52:53], v[6:7]
	v_pk_fma_f32 v[8:9], v[160:161], v[52:53], v[8:9]
	v_pk_fma_f32 v[10:11], v[162:163], v[52:53], v[10:11]
	v_pk_fma_f32 v[12:13], v[164:165], v[52:53], v[12:13]
	v_pk_fma_f32 v[14:15], v[166:167], v[52:53], v[14:15]
	v_pk_fma_f32 v[16:17], v[168:169], v[52:53], v[16:17]
	v_pk_fma_f32 v[22:23], v[170:171], v[52:53], v[22:23]
	v_pk_fma_f32 v[20:21], v[172:173], v[52:53], v[20:21]
	v_pk_fma_f32 v[30:31], v[174:175], v[52:53], v[30:31]
	v_pk_fma_f32 v[28:29], v[176:177], v[52:53], v[28:29]
	v_pk_fma_f32 v[34:35], v[178:179], v[52:53], v[34:35]
	v_pk_fma_f32 v[32:33], v[180:181], v[52:53], v[32:33]
	v_pk_fma_f32 v[38:39], v[182:183], v[52:53], v[38:39]
	v_pk_fma_f32 v[36:37], v[184:185], v[52:53], v[36:37]
	v_pk_fma_f32 v[42:43], v[186:187], v[52:53], v[42:43]
	v_pk_fma_f32 v[40:41], v[188:189], v[52:53], v[40:41]
	v_pk_fma_f32 v[46:47], v[190:191], v[52:53], v[46:47]
	v_pk_fma_f32 v[44:45], v[192:193], v[52:53], v[44:45]
	v_pk_fma_f32 v[50:51], v[194:195], v[52:53], v[50:51]
	v_pk_fma_f32 v[48:49], v[196:197], v[52:53], v[48:49]
	v_pk_fma_f32 v[54:55], v[198:199], v[52:53], v[54:55]
	v_pk_fma_f32 v[52:53], v[200:201], v[52:53], v[2:3]
	s_waitcnt lgkmcnt(2)
	v_lshlrev_b32_e32 v58, 16, v56
	v_and_b32_e32 v59, 0xffff0000, v56
	v_pk_fma_f32 v[24:25], v[148:149], v[58:59], v[24:25]
	v_pk_fma_f32 v[26:27], v[150:151], v[58:59], v[26:27]
	v_pk_fma_f32 v[18:19], v[152:153], v[58:59], v[18:19]
	v_pk_fma_f32 v[4:5], v[154:155], v[58:59], v[4:5]
	v_pk_fma_f32 v[6:7], v[156:157], v[58:59], v[6:7]
	v_pk_fma_f32 v[8:9], v[158:159], v[58:59], v[8:9]
	v_pk_fma_f32 v[10:11], v[160:161], v[58:59], v[10:11]
	v_pk_fma_f32 v[12:13], v[162:163], v[58:59], v[12:13]
	v_pk_fma_f32 v[14:15], v[164:165], v[58:59], v[14:15]
	v_pk_fma_f32 v[16:17], v[166:167], v[58:59], v[16:17]
	v_pk_fma_f32 v[22:23], v[168:169], v[58:59], v[22:23]
	v_pk_fma_f32 v[20:21], v[170:171], v[58:59], v[20:21]
	v_pk_fma_f32 v[30:31], v[172:173], v[58:59], v[30:31]
	v_pk_fma_f32 v[28:29], v[174:175], v[58:59], v[28:29]
	v_pk_fma_f32 v[34:35], v[176:177], v[58:59], v[34:35]
	v_pk_fma_f32 v[32:33], v[178:179], v[58:59], v[32:33]
	v_pk_fma_f32 v[38:39], v[180:181], v[58:59], v[38:39]
	v_pk_fma_f32 v[36:37], v[182:183], v[58:59], v[36:37]
	v_pk_fma_f32 v[42:43], v[184:185], v[58:59], v[42:43]
	v_pk_fma_f32 v[40:41], v[186:187], v[58:59], v[40:41]
	v_pk_fma_f32 v[46:47], v[188:189], v[58:59], v[46:47]
	v_pk_fma_f32 v[44:45], v[190:191], v[58:59], v[44:45]
	v_pk_fma_f32 v[50:51], v[192:193], v[58:59], v[50:51]
	v_pk_fma_f32 v[48:49], v[194:195], v[58:59], v[48:49]
	v_pk_fma_f32 v[54:55], v[196:197], v[58:59], v[54:55]
	v_pk_fma_f32 v[52:53], v[198:199], v[58:59], v[52:53]
	v_pk_fma_f32 v[58:59], v[200:201], v[58:59], v[2:3]
	v_lshlrev_b32_e32 v56, 16, v57
	v_and_b32_e32 v57, 0xffff0000, v57
	v_pk_fma_f32 v[24:25], v[146:147], v[56:57], v[24:25]
	v_pk_fma_f32 v[26:27], v[148:149], v[56:57], v[26:27]
	v_pk_fma_f32 v[18:19], v[150:151], v[56:57], v[18:19]
	v_pk_fma_f32 v[4:5], v[152:153], v[56:57], v[4:5]
	v_pk_fma_f32 v[6:7], v[154:155], v[56:57], v[6:7]
	v_pk_fma_f32 v[8:9], v[156:157], v[56:57], v[8:9]
	v_pk_fma_f32 v[10:11], v[158:159], v[56:57], v[10:11]
	v_pk_fma_f32 v[12:13], v[160:161], v[56:57], v[12:13]
	v_pk_fma_f32 v[14:15], v[162:163], v[56:57], v[14:15]
	v_pk_fma_f32 v[16:17], v[164:165], v[56:57], v[16:17]
	v_pk_fma_f32 v[22:23], v[166:167], v[56:57], v[22:23]
	v_pk_fma_f32 v[20:21], v[168:169], v[56:57], v[20:21]
	v_pk_fma_f32 v[30:31], v[170:171], v[56:57], v[30:31]
	v_pk_fma_f32 v[28:29], v[172:173], v[56:57], v[28:29]
	v_pk_fma_f32 v[34:35], v[174:175], v[56:57], v[34:35]
	v_pk_fma_f32 v[32:33], v[176:177], v[56:57], v[32:33]
	v_pk_fma_f32 v[38:39], v[178:179], v[56:57], v[38:39]
	v_pk_fma_f32 v[36:37], v[180:181], v[56:57], v[36:37]
	v_pk_fma_f32 v[42:43], v[182:183], v[56:57], v[42:43]
	v_pk_fma_f32 v[40:41], v[184:185], v[56:57], v[40:41]
	v_pk_fma_f32 v[46:47], v[186:187], v[56:57], v[46:47]
	v_pk_fma_f32 v[44:45], v[188:189], v[56:57], v[44:45]
	v_pk_fma_f32 v[50:51], v[190:191], v[56:57], v[50:51]
	v_pk_fma_f32 v[48:49], v[192:193], v[56:57], v[48:49]
	v_pk_fma_f32 v[54:55], v[194:195], v[56:57], v[54:55]
	v_pk_fma_f32 v[52:53], v[196:197], v[56:57], v[52:53]
	v_pk_fma_f32 v[58:59], v[198:199], v[56:57], v[58:59]
	v_pk_fma_f32 v[56:57], v[200:201], v[56:57], v[2:3]
	s_waitcnt lgkmcnt(1)
	v_lshlrev_b32_e32 v62, 16, v60
	v_and_b32_e32 v63, 0xffff0000, v60
	v_pk_fma_f32 v[24:25], v[144:145], v[62:63], v[24:25]
	v_pk_fma_f32 v[26:27], v[146:147], v[62:63], v[26:27]
	v_pk_fma_f32 v[18:19], v[148:149], v[62:63], v[18:19]
	v_pk_fma_f32 v[4:5], v[150:151], v[62:63], v[4:5]
	v_pk_fma_f32 v[6:7], v[152:153], v[62:63], v[6:7]
	v_pk_fma_f32 v[8:9], v[154:155], v[62:63], v[8:9]
	v_pk_fma_f32 v[10:11], v[156:157], v[62:63], v[10:11]
	v_pk_fma_f32 v[12:13], v[158:159], v[62:63], v[12:13]
	v_pk_fma_f32 v[14:15], v[160:161], v[62:63], v[14:15]
	v_pk_fma_f32 v[16:17], v[162:163], v[62:63], v[16:17]
	v_pk_fma_f32 v[22:23], v[164:165], v[62:63], v[22:23]
	v_pk_fma_f32 v[20:21], v[166:167], v[62:63], v[20:21]
	v_pk_fma_f32 v[30:31], v[168:169], v[62:63], v[30:31]
	v_pk_fma_f32 v[28:29], v[170:171], v[62:63], v[28:29]
	v_pk_fma_f32 v[34:35], v[172:173], v[62:63], v[34:35]
	v_pk_fma_f32 v[32:33], v[174:175], v[62:63], v[32:33]
	v_pk_fma_f32 v[38:39], v[176:177], v[62:63], v[38:39]
	v_pk_fma_f32 v[36:37], v[178:179], v[62:63], v[36:37]
	v_pk_fma_f32 v[42:43], v[180:181], v[62:63], v[42:43]
	v_pk_fma_f32 v[40:41], v[182:183], v[62:63], v[40:41]
	v_pk_fma_f32 v[46:47], v[184:185], v[62:63], v[46:47]
	v_pk_fma_f32 v[44:45], v[186:187], v[62:63], v[44:45]
	v_pk_fma_f32 v[50:51], v[188:189], v[62:63], v[50:51]
	v_pk_fma_f32 v[48:49], v[190:191], v[62:63], v[48:49]
	v_pk_fma_f32 v[54:55], v[192:193], v[62:63], v[54:55]
	v_pk_fma_f32 v[52:53], v[194:195], v[62:63], v[52:53]
	v_pk_fma_f32 v[58:59], v[196:197], v[62:63], v[58:59]
	v_pk_fma_f32 v[56:57], v[198:199], v[62:63], v[56:57]
	v_pk_fma_f32 v[62:63], v[200:201], v[62:63], v[2:3]
	v_lshlrev_b32_e32 v60, 16, v61
	v_and_b32_e32 v61, 0xffff0000, v61
	v_pk_fma_f32 v[24:25], v[142:143], v[60:61], v[24:25]
	v_pk_fma_f32 v[26:27], v[144:145], v[60:61], v[26:27]
	v_pk_fma_f32 v[18:19], v[146:147], v[60:61], v[18:19]
	v_pk_fma_f32 v[4:5], v[148:149], v[60:61], v[4:5]
	v_pk_fma_f32 v[64:65], v[150:151], v[60:61], v[6:7]
	v_pk_fma_f32 v[8:9], v[152:153], v[60:61], v[8:9]
	v_pk_fma_f32 v[10:11], v[154:155], v[60:61], v[10:11]
	v_pk_fma_f32 v[12:13], v[156:157], v[60:61], v[12:13]
	v_pk_fma_f32 v[14:15], v[158:159], v[60:61], v[14:15]
	v_pk_fma_f32 v[16:17], v[160:161], v[60:61], v[16:17]
	v_pk_fma_f32 v[22:23], v[162:163], v[60:61], v[22:23]
	v_pk_fma_f32 v[20:21], v[164:165], v[60:61], v[20:21]
	v_pk_fma_f32 v[30:31], v[166:167], v[60:61], v[30:31]
	v_pk_fma_f32 v[28:29], v[168:169], v[60:61], v[28:29]
	v_pk_fma_f32 v[34:35], v[170:171], v[60:61], v[34:35]
	v_pk_fma_f32 v[32:33], v[172:173], v[60:61], v[32:33]
	v_pk_fma_f32 v[38:39], v[174:175], v[60:61], v[38:39]
	v_pk_fma_f32 v[36:37], v[176:177], v[60:61], v[36:37]
	v_pk_fma_f32 v[42:43], v[178:179], v[60:61], v[42:43]
	v_pk_fma_f32 v[40:41], v[180:181], v[60:61], v[40:41]
	v_pk_fma_f32 v[46:47], v[182:183], v[60:61], v[46:47]
	v_pk_fma_f32 v[44:45], v[184:185], v[60:61], v[44:45]
	v_pk_fma_f32 v[50:51], v[186:187], v[60:61], v[50:51]
	v_pk_fma_f32 v[48:49], v[188:189], v[60:61], v[48:49]
	v_pk_fma_f32 v[54:55], v[190:191], v[60:61], v[54:55]
	v_pk_fma_f32 v[52:53], v[192:193], v[60:61], v[52:53]
	v_pk_fma_f32 v[58:59], v[194:195], v[60:61], v[58:59]
	v_pk_fma_f32 v[56:57], v[196:197], v[60:61], v[56:57]
	v_pk_fma_f32 v[62:63], v[198:199], v[60:61], v[62:63]
	v_pk_fma_f32 v[60:61], v[200:201], v[60:61], v[2:3]
	s_waitcnt lgkmcnt(0)
	v_lshlrev_b32_e32 v252, 16, v250
	v_and_b32_e32 v253, 0xffff0000, v250
	v_lshlrev_b32_e32 v250, 16, v251
	v_and_b32_e32 v251, 0xffff0000, v251
	v_pk_fma_f32 v[6:7], v[140:141], v[252:253], v[24:25]
	v_pk_fma_f32 v[24:25], v[142:143], v[252:253], v[26:27]
	v_pk_fma_f32 v[18:19], v[144:145], v[252:253], v[18:19]
	v_pk_fma_f32 v[26:27], v[146:147], v[252:253], v[4:5]
	v_pk_fma_f32 v[64:65], v[148:149], v[252:253], v[64:65]
	v_pk_fma_f32 v[8:9], v[150:151], v[252:253], v[8:9]
	v_pk_fma_f32 v[10:11], v[152:153], v[252:253], v[10:11]
	v_pk_fma_f32 v[12:13], v[154:155], v[252:253], v[12:13]
	v_pk_fma_f32 v[14:15], v[156:157], v[252:253], v[14:15]
	v_pk_fma_f32 v[16:17], v[158:159], v[252:253], v[16:17]
	v_pk_fma_f32 v[22:23], v[160:161], v[252:253], v[22:23]
	v_pk_fma_f32 v[20:21], v[162:163], v[252:253], v[20:21]
	v_pk_fma_f32 v[30:31], v[164:165], v[252:253], v[30:31]
	v_pk_fma_f32 v[28:29], v[166:167], v[252:253], v[28:29]
	v_pk_fma_f32 v[34:35], v[168:169], v[252:253], v[34:35]
	v_pk_fma_f32 v[32:33], v[170:171], v[252:253], v[32:33]
	v_pk_fma_f32 v[38:39], v[172:173], v[252:253], v[38:39]
	v_pk_fma_f32 v[36:37], v[174:175], v[252:253], v[36:37]
	v_pk_fma_f32 v[42:43], v[176:177], v[252:253], v[42:43]
	v_pk_fma_f32 v[40:41], v[178:179], v[252:253], v[40:41]
	v_pk_fma_f32 v[46:47], v[180:181], v[252:253], v[46:47]
	v_pk_fma_f32 v[44:45], v[182:183], v[252:253], v[44:45]
	v_pk_fma_f32 v[50:51], v[184:185], v[252:253], v[50:51]
	v_pk_fma_f32 v[48:49], v[186:187], v[252:253], v[48:49]
	v_pk_fma_f32 v[54:55], v[188:189], v[252:253], v[54:55]
	v_pk_fma_f32 v[52:53], v[190:191], v[252:253], v[52:53]
	v_pk_fma_f32 v[58:59], v[192:193], v[252:253], v[58:59]
	v_pk_fma_f32 v[56:57], v[194:195], v[252:253], v[56:57]
	v_pk_fma_f32 v[62:63], v[196:197], v[252:253], v[62:63]
	v_pk_fma_f32 v[60:61], v[198:199], v[252:253], v[60:61]
	v_pk_fma_f32 v[252:253], v[200:201], v[252:253], v[2:3]
	v_pk_fma_f32 v[200:201], v[200:201], v[250:251], v[2:3]
	v_add_u32_e32 v2, 0x10000, v202
	ds_read_b32 v2, v2
	v_pk_fma_f32 v[4:5], v[140:141], v[250:251], v[24:25]
	v_pk_fma_f32 v[18:19], v[142:143], v[250:251], v[18:19]
	v_pk_fma_f32 v[24:25], v[144:145], v[250:251], v[26:27]
	v_pk_fma_f32 v[26:27], v[146:147], v[250:251], v[64:65]
	v_pk_fma_f32 v[8:9], v[148:149], v[250:251], v[8:9]
	v_pk_fma_f32 v[10:11], v[150:151], v[250:251], v[10:11]
	v_pk_fma_f32 v[12:13], v[152:153], v[250:251], v[12:13]
	v_pk_fma_f32 v[14:15], v[154:155], v[250:251], v[14:15]
	v_pk_fma_f32 v[16:17], v[156:157], v[250:251], v[16:17]
	v_pk_fma_f32 v[22:23], v[158:159], v[250:251], v[22:23]
	v_pk_fma_f32 v[20:21], v[160:161], v[250:251], v[20:21]
	v_pk_fma_f32 v[30:31], v[162:163], v[250:251], v[30:31]
	v_pk_fma_f32 v[28:29], v[164:165], v[250:251], v[28:29]
	v_pk_fma_f32 v[34:35], v[166:167], v[250:251], v[34:35]
	v_pk_fma_f32 v[32:33], v[168:169], v[250:251], v[32:33]
	v_pk_fma_f32 v[38:39], v[170:171], v[250:251], v[38:39]
	v_pk_fma_f32 v[36:37], v[172:173], v[250:251], v[36:37]
	v_pk_fma_f32 v[42:43], v[174:175], v[250:251], v[42:43]
	v_pk_fma_f32 v[40:41], v[176:177], v[250:251], v[40:41]
	v_pk_fma_f32 v[46:47], v[178:179], v[250:251], v[46:47]
	v_pk_fma_f32 v[44:45], v[180:181], v[250:251], v[44:45]
	v_pk_fma_f32 v[50:51], v[182:183], v[250:251], v[50:51]
	v_pk_fma_f32 v[48:49], v[184:185], v[250:251], v[48:49]
	v_pk_fma_f32 v[54:55], v[186:187], v[250:251], v[54:55]
	v_pk_fma_f32 v[52:53], v[188:189], v[250:251], v[52:53]
	v_pk_fma_f32 v[58:59], v[190:191], v[250:251], v[58:59]
	v_pk_fma_f32 v[56:57], v[192:193], v[250:251], v[56:57]
	v_pk_fma_f32 v[62:63], v[194:195], v[250:251], v[62:63]
	v_pk_fma_f32 v[60:61], v[196:197], v[250:251], v[60:61]
	v_pk_fma_f32 v[64:65], v[198:199], v[250:251], v[252:253]
	s_waitcnt lgkmcnt(0)
	v_lshlrev_b32_e32 v250, 16, v2
	v_and_b32_e32 v251, 0xffff0000, v2
	v_pk_fma_f32 v[2:3], v[140:141], v[250:251], v[18:19]
	v_pk_fma_f32 v[18:19], v[142:143], v[250:251], v[24:25]
	v_pk_fma_f32 v[24:25], v[144:145], v[250:251], v[26:27]
	v_pk_fma_f32 v[26:27], v[146:147], v[250:251], v[8:9]
	v_add_u32_e32 v8, 0x10800, v202
	ds_read_b32 v8, v8
	v_pk_fma_f32 v[10:11], v[148:149], v[250:251], v[10:11]
	v_pk_fma_f32 v[198:199], v[198:199], v[250:251], v[200:201]
	v_pk_fma_f32 v[12:13], v[150:151], v[250:251], v[12:13]
	v_pk_fma_f32 v[64:65], v[196:197], v[250:251], v[64:65]
	s_waitcnt lgkmcnt(0)
	v_lshlrev_b32_e32 v200, 16, v8
	v_and_b32_e32 v201, 0xffff0000, v8
	v_pk_fma_f32 v[8:9], v[140:141], v[200:201], v[18:19]
	v_pk_fma_f32 v[18:19], v[142:143], v[200:201], v[24:25]
	v_pk_fma_f32 v[24:25], v[144:145], v[200:201], v[26:27]
	v_pk_fma_f32 v[26:27], v[146:147], v[200:201], v[10:11]
	v_add_u32_e32 v10, 0x11000, v202
	ds_read_b32 v10, v10
	v_pk_fma_f32 v[12:13], v[148:149], v[200:201], v[12:13]
	v_pk_fma_f32 v[196:197], v[196:197], v[200:201], v[198:199]
	v_pk_fma_f32 v[14:15], v[152:153], v[250:251], v[14:15]
	v_pk_fma_f32 v[60:61], v[194:195], v[250:251], v[60:61]
	s_waitcnt lgkmcnt(0)
	v_lshlrev_b32_e32 v198, 16, v10
	v_and_b32_e32 v199, 0xffff0000, v10
	v_pk_fma_f32 v[10:11], v[140:141], v[198:199], v[18:19]
	v_pk_fma_f32 v[18:19], v[142:143], v[198:199], v[24:25]
	v_pk_fma_f32 v[24:25], v[144:145], v[198:199], v[26:27]
	v_pk_fma_f32 v[26:27], v[146:147], v[198:199], v[12:13]
	v_add_u32_e32 v12, 0x11800, v202
	ds_read_b32 v12, v12
	v_pk_fma_f32 v[14:15], v[150:151], v[200:201], v[14:15]
	v_pk_fma_f32 v[64:65], v[194:195], v[200:201], v[64:65]
	v_pk_fma_f32 v[14:15], v[148:149], v[198:199], v[14:15]
	v_pk_fma_f32 v[194:195], v[194:195], v[198:199], v[196:197]
	s_waitcnt lgkmcnt(0)
	v_lshlrev_b32_e32 v196, 16, v12
	v_and_b32_e32 v197, 0xffff0000, v12
	v_pk_fma_f32 v[12:13], v[140:141], v[196:197], v[18:19]
	v_pk_fma_f32 v[18:19], v[142:143], v[196:197], v[24:25]
	v_pk_fma_f32 v[24:25], v[144:145], v[196:197], v[26:27]
	v_pk_fma_f32 v[26:27], v[146:147], v[196:197], v[14:15]
	v_add_u32_e32 v14, 0x12000, v202
	ds_read_b32 v14, v14
	v_pk_fma_f32 v[16:17], v[154:155], v[250:251], v[16:17]
	v_pk_fma_f32 v[62:63], v[192:193], v[250:251], v[62:63]
	v_pk_fma_f32 v[16:17], v[152:153], v[200:201], v[16:17]
	v_pk_fma_f32 v[60:61], v[192:193], v[200:201], v[60:61]
	v_pk_fma_f32 v[16:17], v[150:151], v[198:199], v[16:17]
	v_pk_fma_f32 v[64:65], v[192:193], v[198:199], v[64:65]
	v_pk_fma_f32 v[16:17], v[148:149], v[196:197], v[16:17]
	v_pk_fma_f32 v[192:193], v[192:193], v[196:197], v[194:195]
	s_waitcnt lgkmcnt(0)
	v_lshlrev_b32_e32 v194, 16, v14
	v_and_b32_e32 v195, 0xffff0000, v14
	v_pk_fma_f32 v[14:15], v[140:141], v[194:195], v[18:19]
	v_pk_fma_f32 v[18:19], v[142:143], v[194:195], v[24:25]
	v_pk_fma_f32 v[24:25], v[144:145], v[194:195], v[26:27]
	v_pk_fma_f32 v[26:27], v[146:147], v[194:195], v[16:17]
	v_add_u32_e32 v16, 0x12800, v202
	ds_read_b32 v16, v16
	v_pk_fma_f32 v[20:21], v[158:159], v[250:251], v[20:21]
	v_pk_fma_f32 v[56:57], v[190:191], v[250:251], v[56:57]
	v_pk_fma_f32 v[20:21], v[156:157], v[200:201], v[20:21]
	v_pk_fma_f32 v[62:63], v[190:191], v[200:201], v[62:63]
	v_pk_fma_f32 v[20:21], v[154:155], v[198:199], v[20:21]
	v_pk_fma_f32 v[60:61], v[190:191], v[198:199], v[60:61]
	v_pk_fma_f32 v[20:21], v[152:153], v[196:197], v[20:21]
	v_pk_fma_f32 v[64:65], v[190:191], v[196:197], v[64:65]
	v_pk_fma_f32 v[20:21], v[150:151], v[194:195], v[20:21]
	v_pk_fma_f32 v[190:191], v[190:191], v[194:195], v[192:193]
	s_waitcnt lgkmcnt(0)
	v_lshlrev_b32_e32 v192, 16, v16
	v_and_b32_e32 v193, 0xffff0000, v16
	v_pk_fma_f32 v[16:17], v[140:141], v[192:193], v[18:19]
	v_pk_fma_f32 v[18:19], v[142:143], v[192:193], v[24:25]
	v_pk_fma_f32 v[24:25], v[144:145], v[192:193], v[26:27]
	v_pk_fma_f32 v[26:27], v[148:149], v[192:193], v[20:21]
	v_add_u32_e32 v20, 0x13000, v202
	v_pk_fma_f32 v[22:23], v[156:157], v[250:251], v[22:23]
	ds_read_b32 v20, v20
	v_pk_fma_f32 v[22:23], v[154:155], v[200:201], v[22:23]
	v_pk_fma_f32 v[58:59], v[188:189], v[250:251], v[58:59]
	v_pk_fma_f32 v[22:23], v[152:153], v[198:199], v[22:23]
	v_pk_fma_f32 v[56:57], v[188:189], v[200:201], v[56:57]
	v_pk_fma_f32 v[22:23], v[150:151], v[196:197], v[22:23]
	v_pk_fma_f32 v[62:63], v[188:189], v[198:199], v[62:63]
	v_pk_fma_f32 v[22:23], v[148:149], v[194:195], v[22:23]
	v_pk_fma_f32 v[60:61], v[188:189], v[196:197], v[60:61]
	v_pk_fma_f32 v[64:65], v[188:189], v[194:195], v[64:65]
	v_pk_fma_f32 v[22:23], v[146:147], v[192:193], v[22:23]
	v_pk_fma_f32 v[188:189], v[188:189], v[192:193], v[190:191]
	s_waitcnt lgkmcnt(0)
	v_lshlrev_b32_e32 v190, 16, v20
	v_and_b32_e32 v191, 0xffff0000, v20
	v_pk_fma_f32 v[30:31], v[160:161], v[250:251], v[30:31]
	v_pk_fma_f32 v[28:29], v[162:163], v[250:251], v[28:29]
	v_pk_fma_f32 v[34:35], v[164:165], v[250:251], v[34:35]
	v_pk_fma_f32 v[32:33], v[166:167], v[250:251], v[32:33]
	v_pk_fma_f32 v[38:39], v[168:169], v[250:251], v[38:39]
	v_pk_fma_f32 v[36:37], v[170:171], v[250:251], v[36:37]
	v_pk_fma_f32 v[42:43], v[172:173], v[250:251], v[42:43]
	v_pk_fma_f32 v[40:41], v[174:175], v[250:251], v[40:41]
	v_pk_fma_f32 v[46:47], v[176:177], v[250:251], v[46:47]
	v_pk_fma_f32 v[44:45], v[178:179], v[250:251], v[44:45]
	v_pk_fma_f32 v[50:51], v[180:181], v[250:251], v[50:51]
	v_pk_fma_f32 v[48:49], v[182:183], v[250:251], v[48:49]
	v_pk_fma_f32 v[54:55], v[184:185], v[250:251], v[54:55]
	v_pk_fma_f32 v[52:53], v[186:187], v[250:251], v[52:53]
	v_pk_fma_f32 v[20:21], v[142:143], v[190:191], v[24:25]
	v_pk_fma_f32 v[24:25], v[144:145], v[190:191], v[22:23]
	v_add_u32_e32 v22, 0x13800, v202
	v_pk_fma_f32 v[30:31], v[158:159], v[200:201], v[30:31]
	v_pk_fma_f32 v[28:29], v[160:161], v[200:201], v[28:29]
	v_pk_fma_f32 v[34:35], v[162:163], v[200:201], v[34:35]
	v_pk_fma_f32 v[32:33], v[164:165], v[200:201], v[32:33]
	v_pk_fma_f32 v[38:39], v[166:167], v[200:201], v[38:39]
	v_pk_fma_f32 v[36:37], v[168:169], v[200:201], v[36:37]
	v_pk_fma_f32 v[42:43], v[170:171], v[200:201], v[42:43]
	v_pk_fma_f32 v[40:41], v[172:173], v[200:201], v[40:41]
	v_pk_fma_f32 v[46:47], v[174:175], v[200:201], v[46:47]
	v_pk_fma_f32 v[44:45], v[176:177], v[200:201], v[44:45]
	v_pk_fma_f32 v[50:51], v[178:179], v[200:201], v[50:51]
	v_pk_fma_f32 v[48:49], v[180:181], v[200:201], v[48:49]
	v_pk_fma_f32 v[54:55], v[182:183], v[200:201], v[54:55]
	v_pk_fma_f32 v[52:53], v[184:185], v[200:201], v[52:53]
	v_pk_fma_f32 v[58:59], v[186:187], v[200:201], v[58:59]
	ds_read_b32 v22, v22
	v_pk_fma_f32 v[30:31], v[156:157], v[198:199], v[30:31]
	v_pk_fma_f32 v[28:29], v[158:159], v[198:199], v[28:29]
	v_pk_fma_f32 v[34:35], v[160:161], v[198:199], v[34:35]
	v_pk_fma_f32 v[32:33], v[162:163], v[198:199], v[32:33]
	v_pk_fma_f32 v[38:39], v[164:165], v[198:199], v[38:39]
	v_pk_fma_f32 v[36:37], v[166:167], v[198:199], v[36:37]
	v_pk_fma_f32 v[42:43], v[168:169], v[198:199], v[42:43]
	v_pk_fma_f32 v[40:41], v[170:171], v[198:199], v[40:41]
	v_pk_fma_f32 v[46:47], v[172:173], v[198:199], v[46:47]
	v_pk_fma_f32 v[44:45], v[174:175], v[198:199], v[44:45]
	v_pk_fma_f32 v[50:51], v[176:177], v[198:199], v[50:51]
	v_pk_fma_f32 v[48:49], v[178:179], v[198:199], v[48:49]
	v_pk_fma_f32 v[54:55], v[180:181], v[198:199], v[54:55]
	v_pk_fma_f32 v[52:53], v[182:183], v[198:199], v[52:53]
	v_pk_fma_f32 v[58:59], v[184:185], v[198:199], v[58:59]
	v_pk_fma_f32 v[56:57], v[186:187], v[198:199], v[56:57]
	v_pk_fma_f32 v[30:31], v[154:155], v[196:197], v[30:31]
	v_pk_fma_f32 v[28:29], v[156:157], v[196:197], v[28:29]
	v_pk_fma_f32 v[34:35], v[158:159], v[196:197], v[34:35]
	v_pk_fma_f32 v[32:33], v[160:161], v[196:197], v[32:33]
	v_pk_fma_f32 v[38:39], v[162:163], v[196:197], v[38:39]
	v_pk_fma_f32 v[36:37], v[164:165], v[196:197], v[36:37]
	v_pk_fma_f32 v[42:43], v[166:167], v[196:197], v[42:43]
	v_pk_fma_f32 v[40:41], v[168:169], v[196:197], v[40:41]
	v_pk_fma_f32 v[46:47], v[170:171], v[196:197], v[46:47]
	v_pk_fma_f32 v[44:45], v[172:173], v[196:197], v[44:45]
	v_pk_fma_f32 v[50:51], v[174:175], v[196:197], v[50:51]
	v_pk_fma_f32 v[48:49], v[176:177], v[196:197], v[48:49]
	v_pk_fma_f32 v[54:55], v[178:179], v[196:197], v[54:55]
	v_pk_fma_f32 v[52:53], v[180:181], v[196:197], v[52:53]
	v_pk_fma_f32 v[58:59], v[182:183], v[196:197], v[58:59]
	v_pk_fma_f32 v[56:57], v[184:185], v[196:197], v[56:57]
	v_pk_fma_f32 v[62:63], v[186:187], v[196:197], v[62:63]
	v_pk_fma_f32 v[30:31], v[152:153], v[194:195], v[30:31]
	v_pk_fma_f32 v[28:29], v[154:155], v[194:195], v[28:29]
	v_pk_fma_f32 v[34:35], v[156:157], v[194:195], v[34:35]
	v_pk_fma_f32 v[32:33], v[158:159], v[194:195], v[32:33]
	v_pk_fma_f32 v[38:39], v[160:161], v[194:195], v[38:39]
	v_pk_fma_f32 v[36:37], v[162:163], v[194:195], v[36:37]
	v_pk_fma_f32 v[42:43], v[164:165], v[194:195], v[42:43]
	v_pk_fma_f32 v[40:41], v[166:167], v[194:195], v[40:41]
	v_pk_fma_f32 v[46:47], v[168:169], v[194:195], v[46:47]
	v_pk_fma_f32 v[44:45], v[170:171], v[194:195], v[44:45]
	v_pk_fma_f32 v[50:51], v[172:173], v[194:195], v[50:51]
	v_pk_fma_f32 v[48:49], v[174:175], v[194:195], v[48:49]
	v_pk_fma_f32 v[54:55], v[176:177], v[194:195], v[54:55]
	v_pk_fma_f32 v[52:53], v[178:179], v[194:195], v[52:53]
	v_pk_fma_f32 v[58:59], v[180:181], v[194:195], v[58:59]
	v_pk_fma_f32 v[56:57], v[182:183], v[194:195], v[56:57]
	v_pk_fma_f32 v[62:63], v[184:185], v[194:195], v[62:63]
	v_pk_fma_f32 v[60:61], v[186:187], v[194:195], v[60:61]
	v_pk_fma_f32 v[30:31], v[150:151], v[192:193], v[30:31]
	v_pk_fma_f32 v[194:195], v[152:153], v[192:193], v[28:29]
	v_pk_fma_f32 v[34:35], v[154:155], v[192:193], v[34:35]
	v_pk_fma_f32 v[196:197], v[156:157], v[192:193], v[32:33]
	v_pk_fma_f32 v[38:39], v[158:159], v[192:193], v[38:39]
	v_pk_fma_f32 v[198:199], v[160:161], v[192:193], v[36:37]
	v_pk_fma_f32 v[42:43], v[162:163], v[192:193], v[42:43]
	v_pk_fma_f32 v[200:201], v[164:165], v[192:193], v[40:41]
	v_pk_fma_f32 v[46:47], v[166:167], v[192:193], v[46:47]
	v_pk_fma_f32 v[250:251], v[168:169], v[192:193], v[44:45]
	v_pk_fma_f32 v[50:51], v[170:171], v[192:193], v[50:51]
	v_pk_fma_f32 v[252:253], v[172:173], v[192:193], v[48:49]
	v_pk_fma_f32 v[54:55], v[174:175], v[192:193], v[54:55]
	v_pk_fma_f32 v[232:233], v[176:177], v[192:193], v[52:53]
	v_pk_fma_f32 v[58:59], v[178:179], v[192:193], v[58:59]
	v_pk_fma_f32 v[234:235], v[180:181], v[192:193], v[56:57]
	v_pk_fma_f32 v[62:63], v[182:183], v[192:193], v[62:63]
	v_pk_fma_f32 v[236:237], v[184:185], v[192:193], v[60:61]
	v_pk_fma_f32 v[64:65], v[186:187], v[192:193], v[64:65]
	v_pk_fma_f32 v[26:27], v[146:147], v[190:191], v[26:27]
	v_pk_fma_f32 v[28:29], v[148:149], v[190:191], v[30:31]
	v_pk_fma_f32 v[30:31], v[150:151], v[190:191], v[194:195]
	v_pk_fma_f32 v[32:33], v[152:153], v[190:191], v[34:35]
	v_pk_fma_f32 v[34:35], v[154:155], v[190:191], v[196:197]
	v_pk_fma_f32 v[36:37], v[156:157], v[190:191], v[38:39]
	v_pk_fma_f32 v[38:39], v[158:159], v[190:191], v[198:199]
	v_pk_fma_f32 v[40:41], v[160:161], v[190:191], v[42:43]
	v_pk_fma_f32 v[42:43], v[162:163], v[190:191], v[200:201]
	v_pk_fma_f32 v[44:45], v[164:165], v[190:191], v[46:47]
	v_pk_fma_f32 v[46:47], v[166:167], v[190:191], v[250:251]
	v_pk_fma_f32 v[48:49], v[168:169], v[190:191], v[50:51]
	v_pk_fma_f32 v[50:51], v[170:171], v[190:191], v[252:253]
	v_pk_fma_f32 v[52:53], v[172:173], v[190:191], v[54:55]
	v_pk_fma_f32 v[54:55], v[174:175], v[190:191], v[232:233]
	v_pk_fma_f32 v[56:57], v[176:177], v[190:191], v[58:59]
	v_pk_fma_f32 v[58:59], v[178:179], v[190:191], v[234:235]
	v_pk_fma_f32 v[60:61], v[180:181], v[190:191], v[62:63]
	v_pk_fma_f32 v[62:63], v[182:183], v[190:191], v[236:237]
	v_pk_fma_f32 v[64:65], v[184:185], v[190:191], v[64:65]
	v_pk_fma_f32 v[186:187], v[186:187], v[190:191], v[188:189]
	s_waitcnt lgkmcnt(0)
	v_lshlrev_b32_e32 v188, 16, v22
	v_and_b32_e32 v189, 0xffff0000, v22
	v_pk_fma_f32 v[22:23], v[140:141], v[188:189], v[20:21]
	v_pk_fma_f32 v[20:21], v[142:143], v[188:189], v[24:25]
	v_pk_fma_f32 v[24:25], v[144:145], v[188:189], v[26:27]
	v_pk_fma_f32 v[26:27], v[146:147], v[188:189], v[28:29]
	v_pk_fma_f32 v[28:29], v[148:149], v[188:189], v[30:31]
	v_pk_fma_f32 v[30:31], v[150:151], v[188:189], v[32:33]
	v_pk_fma_f32 v[32:33], v[152:153], v[188:189], v[34:35]
	v_pk_fma_f32 v[34:35], v[154:155], v[188:189], v[36:37]
	v_pk_fma_f32 v[36:37], v[156:157], v[188:189], v[38:39]
	v_pk_fma_f32 v[38:39], v[158:159], v[188:189], v[40:41]
	v_pk_fma_f32 v[40:41], v[160:161], v[188:189], v[42:43]
	v_pk_fma_f32 v[42:43], v[162:163], v[188:189], v[44:45]
	v_pk_fma_f32 v[44:45], v[164:165], v[188:189], v[46:47]
	v_pk_fma_f32 v[46:47], v[166:167], v[188:189], v[48:49]
	v_pk_fma_f32 v[48:49], v[168:169], v[188:189], v[50:51]
	v_pk_fma_f32 v[50:51], v[170:171], v[188:189], v[52:53]
	v_pk_fma_f32 v[52:53], v[172:173], v[188:189], v[54:55]
	v_pk_fma_f32 v[54:55], v[174:175], v[188:189], v[56:57]
	v_pk_fma_f32 v[56:57], v[176:177], v[188:189], v[58:59]
	v_pk_fma_f32 v[58:59], v[178:179], v[188:189], v[60:61]
	v_pk_fma_f32 v[60:61], v[180:181], v[188:189], v[62:63]
	v_pk_fma_f32 v[62:63], v[182:183], v[188:189], v[64:65]
	v_pk_fma_f32 v[64:65], v[184:185], v[188:189], v[186:187]
	v_add_u32_e32 v184, 0x14000, v202
	ds_read_b32 v185, v184
	v_pk_fma_f32 v[18:19], v[140:141], v[190:191], v[18:19]
	v_xor_b32_e32 v235, 32, v249
	s_waitcnt lgkmcnt(0)
	v_lshlrev_b32_e32 v184, 16, v185
	v_and_b32_e32 v185, 0xffff0000, v185
	v_pk_fma_f32 v[64:65], v[182:183], v[184:185], v[64:65]
	v_add_u32_e32 v182, 0x14800, v202
	ds_read_b32 v183, v182
	v_pk_fma_f32 v[62:63], v[180:181], v[184:185], v[62:63]
	v_pk_fma_f32 v[60:61], v[178:179], v[184:185], v[60:61]
	v_pk_fma_f32 v[58:59], v[176:177], v[184:185], v[58:59]
	v_pk_fma_f32 v[56:57], v[174:175], v[184:185], v[56:57]
	s_waitcnt lgkmcnt(0)
	v_lshlrev_b32_e32 v182, 16, v183
	v_and_b32_e32 v183, 0xffff0000, v183
	v_pk_fma_f32 v[64:65], v[180:181], v[182:183], v[64:65]
	v_add_u32_e32 v180, 0x15000, v202
	ds_read_b32 v181, v180
	v_pk_fma_f32 v[62:63], v[178:179], v[182:183], v[62:63]
	v_pk_fma_f32 v[60:61], v[176:177], v[182:183], v[60:61]
	v_pk_fma_f32 v[58:59], v[174:175], v[182:183], v[58:59]
	v_pk_fma_f32 v[42:43], v[160:161], v[184:185], v[42:43]
	s_waitcnt lgkmcnt(0)
	v_lshlrev_b32_e32 v180, 16, v181
	v_and_b32_e32 v181, 0xffff0000, v181
	v_pk_fma_f32 v[64:65], v[178:179], v[180:181], v[64:65]
	v_add_u32_e32 v178, 0x15800, v202
	ds_read_b32 v179, v178
	v_pk_fma_f32 v[62:63], v[176:177], v[180:181], v[62:63]
	v_pk_fma_f32 v[60:61], v[174:175], v[180:181], v[60:61]
	v_pk_fma_f32 v[30:31], v[148:149], v[184:185], v[30:31]
	v_pk_fma_f32 v[32:33], v[150:151], v[184:185], v[32:33]
	s_waitcnt lgkmcnt(0)
	v_lshlrev_b32_e32 v178, 16, v179
	v_and_b32_e32 v179, 0xffff0000, v179
	v_pk_fma_f32 v[64:65], v[176:177], v[178:179], v[64:65]
	v_add_u32_e32 v176, 0x16000, v202
	ds_read_b32 v177, v176
	v_pk_fma_f32 v[62:63], v[174:175], v[178:179], v[62:63]
	v_pk_fma_f32 v[34:35], v[152:153], v[184:185], v[34:35]
	v_pk_fma_f32 v[36:37], v[154:155], v[184:185], v[36:37]
	v_pk_fma_f32 v[38:39], v[156:157], v[184:185], v[38:39]
	s_waitcnt lgkmcnt(0)
	v_lshlrev_b32_e32 v176, 16, v177
	v_and_b32_e32 v177, 0xffff0000, v177
	v_pk_fma_f32 v[64:65], v[174:175], v[176:177], v[64:65]
	v_add_u32_e32 v174, 0x16800, v202
	ds_read_b32 v175, v174
	v_pk_fma_f32 v[40:41], v[158:159], v[184:185], v[40:41]
	v_pk_fma_f32 v[44:45], v[162:163], v[184:185], v[44:45]
	v_pk_fma_f32 v[46:47], v[164:165], v[184:185], v[46:47]
	v_pk_fma_f32 v[48:49], v[166:167], v[184:185], v[48:49]
	v_pk_fma_f32 v[50:51], v[168:169], v[184:185], v[50:51]
	v_pk_fma_f32 v[52:53], v[170:171], v[184:185], v[52:53]
	v_pk_fma_f32 v[54:55], v[172:173], v[184:185], v[54:55]
	v_pk_fma_f32 v[42:43], v[158:159], v[182:183], v[42:43]
	v_pk_fma_f32 v[30:31], v[146:147], v[182:183], v[30:31]
	v_pk_fma_f32 v[32:33], v[148:149], v[182:183], v[32:33]
	v_pk_fma_f32 v[34:35], v[150:151], v[182:183], v[34:35]
	v_pk_fma_f32 v[36:37], v[152:153], v[182:183], v[36:37]
	v_pk_fma_f32 v[38:39], v[154:155], v[182:183], v[38:39]
	v_pk_fma_f32 v[40:41], v[156:157], v[182:183], v[40:41]
	v_pk_fma_f32 v[44:45], v[160:161], v[182:183], v[44:45]
	v_pk_fma_f32 v[46:47], v[162:163], v[182:183], v[46:47]
	v_pk_fma_f32 v[48:49], v[164:165], v[182:183], v[48:49]
	v_pk_fma_f32 v[50:51], v[166:167], v[182:183], v[50:51]
	v_pk_fma_f32 v[52:53], v[168:169], v[182:183], v[52:53]
	v_pk_fma_f32 v[54:55], v[170:171], v[182:183], v[54:55]
	v_pk_fma_f32 v[56:57], v[172:173], v[182:183], v[56:57]
	v_pk_fma_f32 v[42:43], v[156:157], v[180:181], v[42:43]
	v_pk_fma_f32 v[30:31], v[144:145], v[180:181], v[30:31]
	v_pk_fma_f32 v[32:33], v[146:147], v[180:181], v[32:33]
	v_pk_fma_f32 v[34:35], v[148:149], v[180:181], v[34:35]
	v_pk_fma_f32 v[36:37], v[150:151], v[180:181], v[36:37]
	v_pk_fma_f32 v[38:39], v[152:153], v[180:181], v[38:39]
	v_pk_fma_f32 v[40:41], v[154:155], v[180:181], v[40:41]
	v_pk_fma_f32 v[44:45], v[158:159], v[180:181], v[44:45]
	v_pk_fma_f32 v[46:47], v[160:161], v[180:181], v[46:47]
	v_pk_fma_f32 v[48:49], v[162:163], v[180:181], v[48:49]
	v_pk_fma_f32 v[50:51], v[164:165], v[180:181], v[50:51]
	v_pk_fma_f32 v[52:53], v[166:167], v[180:181], v[52:53]
	v_pk_fma_f32 v[54:55], v[168:169], v[180:181], v[54:55]
	v_pk_fma_f32 v[56:57], v[170:171], v[180:181], v[56:57]
	v_pk_fma_f32 v[58:59], v[172:173], v[180:181], v[58:59]
	v_pk_fma_f32 v[42:43], v[154:155], v[178:179], v[42:43]
	v_pk_fma_f32 v[30:31], v[142:143], v[178:179], v[30:31]
	v_pk_fma_f32 v[32:33], v[144:145], v[178:179], v[32:33]
	v_pk_fma_f32 v[34:35], v[146:147], v[178:179], v[34:35]
	v_pk_fma_f32 v[36:37], v[148:149], v[178:179], v[36:37]
	v_pk_fma_f32 v[38:39], v[150:151], v[178:179], v[38:39]
	v_pk_fma_f32 v[40:41], v[152:153], v[178:179], v[40:41]
	v_pk_fma_f32 v[44:45], v[156:157], v[178:179], v[44:45]
	v_pk_fma_f32 v[46:47], v[158:159], v[178:179], v[46:47]
	v_pk_fma_f32 v[48:49], v[160:161], v[178:179], v[48:49]
	v_pk_fma_f32 v[50:51], v[162:163], v[178:179], v[50:51]
	v_pk_fma_f32 v[52:53], v[164:165], v[178:179], v[52:53]
	v_pk_fma_f32 v[54:55], v[166:167], v[178:179], v[54:55]
	v_pk_fma_f32 v[56:57], v[168:169], v[178:179], v[56:57]
	v_pk_fma_f32 v[58:59], v[170:171], v[178:179], v[58:59]
	v_pk_fma_f32 v[60:61], v[172:173], v[178:179], v[60:61]
	v_pk_fma_f32 v[42:43], v[152:153], v[176:177], v[42:43]
	s_waitcnt lgkmcnt(0)
	v_lshlrev_b32_e32 v174, 16, v175
	v_and_b32_e32 v175, 0xffff0000, v175
	v_pk_fma_f32 v[30:31], v[140:141], v[176:177], v[30:31]
	v_pk_fma_f32 v[32:33], v[142:143], v[176:177], v[32:33]
	v_pk_fma_f32 v[34:35], v[144:145], v[176:177], v[34:35]
	v_pk_fma_f32 v[36:37], v[146:147], v[176:177], v[36:37]
	v_pk_fma_f32 v[38:39], v[148:149], v[176:177], v[38:39]
	v_pk_fma_f32 v[40:41], v[150:151], v[176:177], v[40:41]
	v_pk_fma_f32 v[44:45], v[154:155], v[176:177], v[44:45]
	v_pk_fma_f32 v[46:47], v[156:157], v[176:177], v[46:47]
	v_pk_fma_f32 v[48:49], v[158:159], v[176:177], v[48:49]
	v_pk_fma_f32 v[50:51], v[160:161], v[176:177], v[50:51]
	v_pk_fma_f32 v[52:53], v[162:163], v[176:177], v[52:53]
	v_pk_fma_f32 v[54:55], v[164:165], v[176:177], v[54:55]
	v_pk_fma_f32 v[56:57], v[166:167], v[176:177], v[56:57]
	v_pk_fma_f32 v[58:59], v[168:169], v[176:177], v[58:59]
	v_pk_fma_f32 v[60:61], v[170:171], v[176:177], v[60:61]
	v_pk_fma_f32 v[62:63], v[172:173], v[176:177], v[62:63]
	v_pk_fma_f32 v[176:177], v[150:151], v[174:175], v[42:43]
	v_add_u32_e32 v42, 0x17000, v202
	ds_read_b32 v42, v42
	v_pk_fma_f32 v[28:29], v[146:147], v[184:185], v[28:29]
	v_pk_fma_f32 v[26:27], v[144:145], v[184:185], v[26:27]
	v_pk_fma_f32 v[28:29], v[144:145], v[182:183], v[28:29]
	v_pk_fma_f32 v[24:25], v[142:143], v[184:185], v[24:25]
	v_pk_fma_f32 v[26:27], v[142:143], v[182:183], v[26:27]
	v_pk_fma_f32 v[28:29], v[142:143], v[180:181], v[28:29]
	v_pk_fma_f32 v[20:21], v[140:141], v[184:185], v[20:21]
	v_pk_fma_f32 v[24:25], v[140:141], v[182:183], v[24:25]
	v_pk_fma_f32 v[26:27], v[140:141], v[180:181], v[26:27]
	v_pk_fma_f32 v[28:29], v[140:141], v[178:179], v[28:29]
	v_pk_fma_f32 v[32:33], v[140:141], v[174:175], v[32:33]
	v_pk_fma_f32 v[34:35], v[142:143], v[174:175], v[34:35]
	v_pk_fma_f32 v[36:37], v[144:145], v[174:175], v[36:37]
	v_pk_fma_f32 v[38:39], v[146:147], v[174:175], v[38:39]
	v_pk_fma_f32 v[40:41], v[148:149], v[174:175], v[40:41]
	v_pk_fma_f32 v[178:179], v[152:153], v[174:175], v[44:45]
	v_pk_fma_f32 v[180:181], v[154:155], v[174:175], v[46:47]
	v_pk_fma_f32 v[182:183], v[156:157], v[174:175], v[48:49]
	v_pk_fma_f32 v[184:185], v[158:159], v[174:175], v[50:51]
	v_pk_fma_f32 v[186:187], v[160:161], v[174:175], v[52:53]
	v_pk_fma_f32 v[188:189], v[162:163], v[174:175], v[54:55]
	v_pk_fma_f32 v[190:191], v[164:165], v[174:175], v[56:57]
	v_pk_fma_f32 v[192:193], v[166:167], v[174:175], v[58:59]
	v_pk_fma_f32 v[194:195], v[168:169], v[174:175], v[60:61]
	v_pk_fma_f32 v[196:197], v[170:171], v[174:175], v[62:63]
	v_pk_fma_f32 v[172:173], v[172:173], v[174:175], v[64:65]
	s_waitcnt lgkmcnt(0)
	v_lshlrev_b32_e32 v174, 16, v42
	v_and_b32_e32 v175, 0xffff0000, v42
	v_pk_fma_f32 v[42:43], v[146:147], v[174:175], v[40:41]
	v_add_u32_e32 v40, 0x17800, v202
	ds_read_b32 v40, v40
	v_pk_fma_f32 v[36:37], v[142:143], v[174:175], v[36:37]
	v_pk_fma_f32 v[38:39], v[144:145], v[174:175], v[38:39]
	v_pk_fma_f32 v[170:171], v[170:171], v[174:175], v[172:173]
	s_waitcnt lgkmcnt(0)
	v_lshlrev_b32_e32 v172, 16, v40
	v_and_b32_e32 v173, 0xffff0000, v40
	v_pk_fma_f32 v[40:41], v[140:141], v[172:173], v[36:37]
	v_pk_fma_f32 v[36:37], v[142:143], v[172:173], v[38:39]
	v_add_u32_e32 v38, 0x18000, v202
	ds_read_b32 v38, v38
	v_pk_fma_f32 v[44:45], v[148:149], v[174:175], v[176:177]
	v_pk_fma_f32 v[46:47], v[150:151], v[174:175], v[178:179]
	v_pk_fma_f32 v[48:49], v[152:153], v[174:175], v[180:181]
	v_pk_fma_f32 v[50:51], v[154:155], v[174:175], v[182:183]
	v_pk_fma_f32 v[52:53], v[156:157], v[174:175], v[184:185]
	v_pk_fma_f32 v[54:55], v[158:159], v[174:175], v[186:187]
	v_pk_fma_f32 v[56:57], v[160:161], v[174:175], v[188:189]
	v_pk_fma_f32 v[58:59], v[162:163], v[174:175], v[190:191]
	v_pk_fma_f32 v[60:61], v[164:165], v[174:175], v[192:193]
	v_pk_fma_f32 v[62:63], v[166:167], v[174:175], v[194:195]
	v_pk_fma_f32 v[64:65], v[168:169], v[174:175], v[196:197]
	v_pk_fma_f32 v[42:43], v[144:145], v[172:173], v[42:43]
	v_pk_fma_f32 v[44:45], v[146:147], v[172:173], v[44:45]
	v_pk_fma_f32 v[46:47], v[148:149], v[172:173], v[46:47]
	v_pk_fma_f32 v[48:49], v[150:151], v[172:173], v[48:49]
	v_pk_fma_f32 v[50:51], v[152:153], v[172:173], v[50:51]
	v_pk_fma_f32 v[52:53], v[154:155], v[172:173], v[52:53]
	v_pk_fma_f32 v[54:55], v[156:157], v[172:173], v[54:55]
	v_pk_fma_f32 v[56:57], v[158:159], v[172:173], v[56:57]
	v_pk_fma_f32 v[58:59], v[160:161], v[172:173], v[58:59]
	v_pk_fma_f32 v[60:61], v[162:163], v[172:173], v[60:61]
	v_pk_fma_f32 v[62:63], v[164:165], v[172:173], v[62:63]
	v_pk_fma_f32 v[64:65], v[166:167], v[172:173], v[64:65]
	v_pk_fma_f32 v[168:169], v[168:169], v[172:173], v[170:171]
	s_waitcnt lgkmcnt(0)
	v_lshlrev_b32_e32 v170, 16, v38
	v_and_b32_e32 v171, 0xffff0000, v38
	v_pk_fma_f32 v[38:39], v[140:141], v[170:171], v[36:37]
	v_pk_fma_f32 v[36:37], v[142:143], v[170:171], v[42:43]
	v_pk_fma_f32 v[42:43], v[144:145], v[170:171], v[44:45]
	v_pk_fma_f32 v[44:45], v[146:147], v[170:171], v[46:47]
	v_pk_fma_f32 v[46:47], v[148:149], v[170:171], v[48:49]
	v_pk_fma_f32 v[48:49], v[150:151], v[170:171], v[50:51]
	v_pk_fma_f32 v[50:51], v[152:153], v[170:171], v[52:53]
	v_pk_fma_f32 v[52:53], v[154:155], v[170:171], v[54:55]
	v_pk_fma_f32 v[54:55], v[156:157], v[170:171], v[56:57]
	v_pk_fma_f32 v[56:57], v[158:159], v[170:171], v[58:59]
	v_pk_fma_f32 v[58:59], v[160:161], v[170:171], v[60:61]
	v_pk_fma_f32 v[60:61], v[162:163], v[170:171], v[62:63]
	v_pk_fma_f32 v[62:63], v[164:165], v[170:171], v[64:65]
	v_pk_fma_f32 v[64:65], v[166:167], v[170:171], v[168:169]
	v_add_u32_e32 v166, 0x18800, v202
	ds_read_b32 v167, v166
	v_pk_fma_f32 v[34:35], v[140:141], v[174:175], v[34:35]
	v_add_f32_e32 v168, v28, v29
	v_add_f32_e32 v170, v30, v31
	v_add_f32_e32 v172, v32, v33
	s_waitcnt lgkmcnt(0)
	v_lshlrev_b32_e32 v166, 16, v167
	v_and_b32_e32 v167, 0xffff0000, v167
	v_pk_fma_f32 v[64:65], v[164:165], v[166:167], v[64:65]
	v_add_u32_e32 v164, 0x19000, v202
	ds_read_b32 v165, v164
	v_pk_fma_f32 v[62:63], v[162:163], v[166:167], v[62:63]
	v_pk_fma_f32 v[60:61], v[160:161], v[166:167], v[60:61]
	v_pk_fma_f32 v[58:59], v[158:159], v[166:167], v[58:59]
	v_pk_fma_f32 v[56:57], v[156:157], v[166:167], v[56:57]
	s_waitcnt lgkmcnt(0)
	v_lshlrev_b32_e32 v164, 16, v165
	v_and_b32_e32 v165, 0xffff0000, v165
	v_pk_fma_f32 v[64:65], v[162:163], v[164:165], v[64:65]
	v_add_u32_e32 v162, 0x19800, v202
	ds_read_b32 v163, v162
	v_pk_fma_f32 v[62:63], v[160:161], v[164:165], v[62:63]
	v_pk_fma_f32 v[60:61], v[158:159], v[164:165], v[60:61]
	v_pk_fma_f32 v[58:59], v[156:157], v[164:165], v[58:59]
	v_pk_fma_f32 v[48:49], v[148:149], v[166:167], v[48:49]
	s_waitcnt lgkmcnt(0)
	v_lshlrev_b32_e32 v162, 16, v163
	v_and_b32_e32 v163, 0xffff0000, v163
	v_pk_fma_f32 v[64:65], v[160:161], v[162:163], v[64:65]
	v_add_u32_e32 v160, 0x1a000, v202
	ds_read_b32 v161, v160
	v_pk_fma_f32 v[62:63], v[158:159], v[162:163], v[62:63]
	v_pk_fma_f32 v[60:61], v[156:157], v[162:163], v[60:61]
	v_pk_fma_f32 v[50:51], v[150:151], v[166:167], v[50:51]
	v_pk_fma_f32 v[52:53], v[152:153], v[166:167], v[52:53]
	s_waitcnt lgkmcnt(0)
	v_lshlrev_b32_e32 v160, 16, v161
	v_and_b32_e32 v161, 0xffff0000, v161
	v_pk_fma_f32 v[64:65], v[158:159], v[160:161], v[64:65]
	v_add_u32_e32 v158, 0x1a800, v202
	ds_read_b32 v159, v158
	v_pk_fma_f32 v[62:63], v[156:157], v[160:161], v[62:63]
	v_pk_fma_f32 v[54:55], v[154:155], v[166:167], v[54:55]
	v_pk_fma_f32 v[48:49], v[146:147], v[164:165], v[48:49]
	v_pk_fma_f32 v[50:51], v[148:149], v[164:165], v[50:51]
	s_waitcnt lgkmcnt(0)
	v_lshlrev_b32_e32 v158, 16, v159
	v_and_b32_e32 v159, 0xffff0000, v159
	v_pk_fma_f32 v[156:157], v[156:157], v[158:159], v[64:65]
	v_add_u32_e32 v64, 0x1b000, v202
	ds_read_b32 v64, v64
	v_pk_fma_f32 v[52:53], v[150:151], v[164:165], v[52:53]
	v_pk_fma_f32 v[54:55], v[152:153], v[164:165], v[54:55]
	v_pk_fma_f32 v[56:57], v[154:155], v[164:165], v[56:57]
	v_pk_fma_f32 v[48:49], v[144:145], v[162:163], v[48:49]
	v_pk_fma_f32 v[50:51], v[146:147], v[162:163], v[50:51]
	v_pk_fma_f32 v[52:53], v[148:149], v[162:163], v[52:53]
	v_pk_fma_f32 v[54:55], v[150:151], v[162:163], v[54:55]
	v_pk_fma_f32 v[56:57], v[152:153], v[162:163], v[56:57]
	v_pk_fma_f32 v[58:59], v[154:155], v[162:163], v[58:59]
	v_pk_fma_f32 v[48:49], v[142:143], v[160:161], v[48:49]
	v_pk_fma_f32 v[50:51], v[144:145], v[160:161], v[50:51]
	v_pk_fma_f32 v[52:53], v[146:147], v[160:161], v[52:53]
	v_pk_fma_f32 v[54:55], v[148:149], v[160:161], v[54:55]
	v_pk_fma_f32 v[56:57], v[150:151], v[160:161], v[56:57]
	v_pk_fma_f32 v[58:59], v[152:153], v[160:161], v[58:59]
	v_pk_fma_f32 v[60:61], v[154:155], v[160:161], v[60:61]
	v_pk_fma_f32 v[48:49], v[140:141], v[158:159], v[48:49]
	v_pk_fma_f32 v[50:51], v[142:143], v[158:159], v[50:51]
	v_pk_fma_f32 v[52:53], v[144:145], v[158:159], v[52:53]
	v_pk_fma_f32 v[54:55], v[146:147], v[158:159], v[54:55]
	v_pk_fma_f32 v[56:57], v[148:149], v[158:159], v[56:57]
	v_pk_fma_f32 v[58:59], v[150:151], v[158:159], v[58:59]
	v_pk_fma_f32 v[60:61], v[152:153], v[158:159], v[60:61]
	v_pk_fma_f32 v[62:63], v[154:155], v[158:159], v[62:63]
	s_waitcnt lgkmcnt(0)
	v_lshlrev_b32_e32 v158, 16, v64
	v_and_b32_e32 v159, 0xffff0000, v64
	v_pk_fma_f32 v[64:65], v[152:153], v[158:159], v[62:63]
	v_add_u32_e32 v62, 0x1b800, v202
	ds_read_b32 v62, v62
	v_pk_fma_f32 v[52:53], v[142:143], v[158:159], v[52:53]
	v_pk_fma_f32 v[54:55], v[144:145], v[158:159], v[54:55]
	v_pk_fma_f32 v[56:57], v[146:147], v[158:159], v[56:57]
	v_pk_fma_f32 v[154:155], v[154:155], v[158:159], v[156:157]
	s_waitcnt lgkmcnt(0)
	v_lshlrev_b32_e32 v156, 16, v62
	v_and_b32_e32 v157, 0xffff0000, v62
	v_pk_fma_f32 v[62:63], v[140:141], v[156:157], v[52:53]
	v_pk_fma_f32 v[52:53], v[142:143], v[156:157], v[54:55]
	v_pk_fma_f32 v[54:55], v[144:145], v[156:157], v[56:57]
	v_add_u32_e32 v56, 0x1c000, v202
	ds_read_b32 v56, v56
	v_pk_fma_f32 v[58:59], v[148:149], v[158:159], v[58:59]
	v_pk_fma_f32 v[60:61], v[150:151], v[158:159], v[60:61]
	v_pk_fma_f32 v[58:59], v[146:147], v[156:157], v[58:59]
	v_pk_fma_f32 v[60:61], v[148:149], v[156:157], v[60:61]
	v_pk_fma_f32 v[64:65], v[150:151], v[156:157], v[64:65]
	v_pk_fma_f32 v[152:153], v[152:153], v[156:157], v[154:155]
	s_waitcnt lgkmcnt(0)
	v_lshlrev_b32_e32 v154, 16, v56
	v_and_b32_e32 v155, 0xffff0000, v56
	v_pk_fma_f32 v[56:57], v[140:141], v[154:155], v[52:53]
	v_pk_fma_f32 v[52:53], v[142:143], v[154:155], v[54:55]
	v_pk_fma_f32 v[54:55], v[144:145], v[154:155], v[58:59]
	v_pk_fma_f32 v[58:59], v[146:147], v[154:155], v[60:61]
	v_pk_fma_f32 v[60:61], v[148:149], v[154:155], v[64:65]
	v_pk_fma_f32 v[64:65], v[150:151], v[154:155], v[152:153]
	v_add_u32_e32 v150, 0x1c800, v202
	ds_read_b32 v151, v150
	v_pk_fma_f32 v[46:47], v[146:147], v[166:167], v[46:47]
	v_pk_fma_f32 v[44:45], v[144:145], v[166:167], v[44:45]
	v_pk_fma_f32 v[46:47], v[144:145], v[164:165], v[46:47]
	v_pk_fma_f32 v[42:43], v[142:143], v[166:167], v[42:43]
	s_waitcnt lgkmcnt(0)
	v_lshlrev_b32_e32 v150, 16, v151
	v_and_b32_e32 v151, 0xffff0000, v151
	v_pk_fma_f32 v[152:153], v[146:147], v[150:151], v[60:61]
	v_add_u32_e32 v60, 0x1d000, v202
	ds_read_b32 v60, v60
	v_pk_fma_f32 v[54:55], v[142:143], v[150:151], v[54:55]
	v_pk_fma_f32 v[58:59], v[144:145], v[150:151], v[58:59]
	v_pk_fma_f32 v[64:65], v[148:149], v[150:151], v[64:65]
	v_pk_fma_f32 v[52:53], v[140:141], v[150:151], v[52:53]
	s_waitcnt lgkmcnt(0)
	v_lshlrev_b32_e32 v148, 16, v60
	v_and_b32_e32 v149, 0xffff0000, v60
	v_pk_fma_f32 v[60:61], v[140:141], v[148:149], v[54:55]
	v_pk_fma_f32 v[54:55], v[142:143], v[148:149], v[58:59]
	ds_read_b32 v58, v203
	v_pk_fma_f32 v[64:65], v[146:147], v[148:149], v[64:65]
	v_pk_fma_f32 v[150:151], v[144:145], v[148:149], v[152:153]
	v_pk_fma_f32 v[44:45], v[142:143], v[164:165], v[44:45]
	v_pk_fma_f32 v[46:47], v[142:143], v[162:163], v[46:47]
	s_waitcnt lgkmcnt(0)
	v_lshlrev_b32_e32 v146, 16, v58
	v_and_b32_e32 v147, 0xffff0000, v58
	v_pk_fma_f32 v[64:65], v[144:145], v[146:147], v[64:65]
	ds_read_b32 v145, v204
	v_pk_fma_f32 v[58:59], v[140:141], v[146:147], v[54:55]
	v_pk_fma_f32 v[54:55], v[142:143], v[146:147], v[150:151]
	v_pk_fma_f32 v[36:37], v[140:141], v[166:167], v[36:37]
	v_pk_fma_f32 v[42:43], v[140:141], v[164:165], v[42:43]
	s_waitcnt lgkmcnt(0)
	v_lshlrev_b32_e32 v144, 16, v145
	v_and_b32_e32 v145, 0xffff0000, v145
	v_pk_fma_f32 v[64:65], v[142:143], v[144:145], v[64:65]
	ds_read_b32 v143, v205
	v_pk_fma_f32 v[44:45], v[140:141], v[162:163], v[44:45]
	v_pk_fma_f32 v[46:47], v[140:141], v[160:161], v[46:47]
	v_pk_fma_f32 v[50:51], v[140:141], v[158:159], v[50:51]
	v_pk_fma_f32 v[54:55], v[140:141], v[144:145], v[54:55]
	s_waitcnt lgkmcnt(0)
	v_lshlrev_b32_e32 v142, 16, v143
	v_and_b32_e32 v143, 0xffff0000, v143
	v_pk_fma_f32 v[64:65], v[140:141], v[142:143], v[64:65]
	v_xor_b32_e32 v236, 32, v249
	v_lshlrev_b32_e32 v236, 2, v236
	v_pk_mul_f32 v[250:251], v[6:7], v[6:7]
	v_add_f32_e32 v234, v6, v7
	v_add_f32_e32 v235, v250, v251
	v_cndmask_b32_e64 v140, v234, v235, s[4:5]
	v_cndmask_b32_e64 v141, v235, v234, s[4:5]
	ds_bpermute_b32 v140, v236, v140
	v_pk_mul_f32 v[250:251], v[4:5], v[4:5]
	v_add_f32_e32 v234, v4, v5
	v_add_f32_e32 v235, v250, v251
	v_cndmask_b32_e64 v142, v234, v235, s[4:5]
	v_cndmask_b32_e64 v143, v235, v234, s[4:5]
	ds_bpermute_b32 v142, v236, v142
	v_pk_mul_f32 v[250:251], v[2:3], v[2:3]
	v_add_f32_e32 v234, v2, v3
	v_add_f32_e32 v235, v250, v251
	v_cndmask_b32_e64 v144, v234, v235, s[4:5]
	v_cndmask_b32_e64 v145, v235, v234, s[4:5]
	ds_bpermute_b32 v144, v236, v144
	v_pk_mul_f32 v[250:251], v[8:9], v[8:9]
	v_add_f32_e32 v234, v8, v9
	v_add_f32_e32 v235, v250, v251
	v_cndmask_b32_e64 v146, v234, v235, s[4:5]
	v_cndmask_b32_e64 v147, v235, v234, s[4:5]
	ds_bpermute_b32 v146, v236, v146
	v_pk_mul_f32 v[250:251], v[10:11], v[10:11]
	v_add_f32_e32 v234, v10, v11
	v_add_f32_e32 v235, v250, v251
	v_cndmask_b32_e64 v148, v234, v235, s[4:5]
	v_cndmask_b32_e64 v149, v235, v234, s[4:5]
	ds_bpermute_b32 v148, v236, v148
	v_pk_mul_f32 v[250:251], v[12:13], v[12:13]
	v_add_f32_e32 v234, v12, v13
	v_add_f32_e32 v235, v250, v251
	v_cndmask_b32_e64 v150, v234, v235, s[4:5]
	v_cndmask_b32_e64 v151, v235, v234, s[4:5]
	ds_bpermute_b32 v150, v236, v150
	v_pk_mul_f32 v[250:251], v[14:15], v[14:15]
	v_add_f32_e32 v234, v14, v15
	v_add_f32_e32 v235, v250, v251
	v_cndmask_b32_e64 v152, v234, v235, s[4:5]
	v_cndmask_b32_e64 v153, v235, v234, s[4:5]
	ds_bpermute_b32 v152, v236, v152
	v_pk_mul_f32 v[250:251], v[16:17], v[16:17]
	v_add_f32_e32 v234, v16, v17
	v_add_f32_e32 v235, v250, v251
	v_cndmask_b32_e64 v154, v234, v235, s[4:5]
	v_cndmask_b32_e64 v155, v235, v234, s[4:5]
	ds_bpermute_b32 v154, v236, v154
	v_pk_mul_f32 v[250:251], v[18:19], v[18:19]
	v_add_f32_e32 v234, v18, v19
	v_add_f32_e32 v235, v250, v251
	v_cndmask_b32_e64 v156, v234, v235, s[4:5]
	v_cndmask_b32_e64 v157, v235, v234, s[4:5]
	ds_bpermute_b32 v156, v236, v156
	v_pk_mul_f32 v[250:251], v[22:23], v[22:23]
	v_add_f32_e32 v234, v22, v23
	v_add_f32_e32 v235, v250, v251
	v_cndmask_b32_e64 v158, v234, v235, s[4:5]
	v_cndmask_b32_e64 v159, v235, v234, s[4:5]
	ds_bpermute_b32 v158, v236, v158
	v_pk_mul_f32 v[250:251], v[20:21], v[20:21]
	v_add_f32_e32 v234, v20, v21
	v_add_f32_e32 v235, v250, v251
	v_cndmask_b32_e64 v160, v234, v235, s[4:5]
	v_cndmask_b32_e64 v161, v235, v234, s[4:5]
	ds_bpermute_b32 v160, v236, v160
	v_pk_mul_f32 v[250:251], v[24:25], v[24:25]
	v_add_f32_e32 v234, v24, v25
	v_add_f32_e32 v235, v250, v251
	v_cndmask_b32_e64 v162, v234, v235, s[4:5]
	v_cndmask_b32_e64 v163, v235, v234, s[4:5]
	ds_bpermute_b32 v162, v236, v162
	v_pk_mul_f32 v[250:251], v[26:27], v[26:27]
	v_add_f32_e32 v234, v26, v27
	v_add_f32_e32 v235, v250, v251
	v_cndmask_b32_e64 v164, v234, v235, s[4:5]
	v_cndmask_b32_e64 v165, v235, v234, s[4:5]
	ds_bpermute_b32 v164, v236, v164
	v_pk_mul_f32 v[250:251], v[28:29], v[28:29]
	v_add_f32_e32 v234, v28, v29
	v_add_f32_e32 v235, v250, v251
	v_cndmask_b32_e64 v166, v234, v235, s[4:5]
	v_cndmask_b32_e64 v167, v235, v234, s[4:5]
	ds_bpermute_b32 v166, v236, v166
	v_pk_mul_f32 v[250:251], v[30:31], v[30:31]
	v_add_f32_e32 v234, v30, v31
	v_add_f32_e32 v235, v250, v251
	v_cndmask_b32_e64 v168, v234, v235, s[4:5]
	v_cndmask_b32_e64 v169, v235, v234, s[4:5]
	ds_bpermute_b32 v168, v236, v168
	v_pk_mul_f32 v[250:251], v[32:33], v[32:33]
	v_add_f32_e32 v234, v32, v33
	v_add_f32_e32 v235, v250, v251
	v_cndmask_b32_e64 v170, v234, v235, s[4:5]
	v_cndmask_b32_e64 v171, v235, v234, s[4:5]
	ds_bpermute_b32 v170, v236, v170
	s_waitcnt lgkmcnt(0)
	v_add_f32_e32 v140, v141, v140
	v_add_f32_e32 v142, v143, v142
	v_add_f32_e32 v144, v145, v144
	v_add_f32_e32 v146, v147, v146
	v_add_f32_e32 v148, v149, v148
	v_add_f32_e32 v150, v151, v150
	v_add_f32_e32 v152, v153, v152
	v_add_f32_e32 v154, v155, v154
	v_add_f32_e32 v156, v157, v156
	v_add_f32_e32 v158, v159, v158
	v_add_f32_e32 v160, v161, v160
	v_add_f32_e32 v162, v163, v162
	v_add_f32_e32 v164, v165, v164
	v_add_f32_e32 v166, v167, v166
	v_add_f32_e32 v168, v169, v168
	v_add_f32_e32 v170, v171, v170
	v_pk_mul_f32 v[250:251], v[34:35], v[34:35]
	v_add_f32_e32 v234, v34, v35
	v_add_f32_e32 v235, v250, v251
	v_cndmask_b32_e64 v172, v234, v235, s[4:5]
	v_cndmask_b32_e64 v173, v235, v234, s[4:5]
	ds_bpermute_b32 v172, v236, v172
	v_pk_mul_f32 v[250:251], v[40:41], v[40:41]
	v_add_f32_e32 v234, v40, v41
	v_add_f32_e32 v235, v250, v251
	v_cndmask_b32_e64 v174, v234, v235, s[4:5]
	v_cndmask_b32_e64 v175, v235, v234, s[4:5]
	ds_bpermute_b32 v174, v236, v174
	v_pk_mul_f32 v[250:251], v[38:39], v[38:39]
	v_add_f32_e32 v234, v38, v39
	v_add_f32_e32 v235, v250, v251
	v_cndmask_b32_e64 v176, v234, v235, s[4:5]
	v_cndmask_b32_e64 v177, v235, v234, s[4:5]
	ds_bpermute_b32 v176, v236, v176
	v_pk_mul_f32 v[250:251], v[36:37], v[36:37]
	v_add_f32_e32 v234, v36, v37
	v_add_f32_e32 v235, v250, v251
	v_cndmask_b32_e64 v178, v234, v235, s[4:5]
	v_cndmask_b32_e64 v179, v235, v234, s[4:5]
	ds_bpermute_b32 v178, v236, v178
	v_pk_mul_f32 v[250:251], v[42:43], v[42:43]
	v_add_f32_e32 v234, v42, v43
	v_add_f32_e32 v235, v250, v251
	v_cndmask_b32_e64 v180, v234, v235, s[4:5]
	v_cndmask_b32_e64 v181, v235, v234, s[4:5]
	ds_bpermute_b32 v180, v236, v180
	v_pk_mul_f32 v[250:251], v[44:45], v[44:45]
	v_add_f32_e32 v234, v44, v45
	v_add_f32_e32 v235, v250, v251
	v_cndmask_b32_e64 v182, v234, v235, s[4:5]
	v_cndmask_b32_e64 v183, v235, v234, s[4:5]
	ds_bpermute_b32 v182, v236, v182
	v_pk_mul_f32 v[250:251], v[46:47], v[46:47]
	v_add_f32_e32 v234, v46, v47
	v_add_f32_e32 v235, v250, v251
	v_cndmask_b32_e64 v184, v234, v235, s[4:5]
	v_cndmask_b32_e64 v185, v235, v234, s[4:5]
	ds_bpermute_b32 v184, v236, v184
	v_pk_mul_f32 v[250:251], v[48:49], v[48:49]
	v_add_f32_e32 v234, v48, v49
	v_add_f32_e32 v235, v250, v251
	v_cndmask_b32_e64 v186, v234, v235, s[4:5]
	v_cndmask_b32_e64 v187, v235, v234, s[4:5]
	ds_bpermute_b32 v186, v236, v186
	v_pk_mul_f32 v[250:251], v[50:51], v[50:51]
	v_add_f32_e32 v234, v50, v51
	v_add_f32_e32 v235, v250, v251
	v_cndmask_b32_e64 v188, v234, v235, s[4:5]
	v_cndmask_b32_e64 v189, v235, v234, s[4:5]
	ds_bpermute_b32 v188, v236, v188
	v_pk_mul_f32 v[250:251], v[62:63], v[62:63]
	v_add_f32_e32 v234, v62, v63
	v_add_f32_e32 v235, v250, v251
	v_cndmask_b32_e64 v190, v234, v235, s[4:5]
	v_cndmask_b32_e64 v191, v235, v234, s[4:5]
	ds_bpermute_b32 v190, v236, v190
	v_pk_mul_f32 v[250:251], v[56:57], v[56:57]
	v_add_f32_e32 v234, v56, v57
	v_add_f32_e32 v235, v250, v251
	v_cndmask_b32_e64 v192, v234, v235, s[4:5]
	v_cndmask_b32_e64 v193, v235, v234, s[4:5]
	ds_bpermute_b32 v192, v236, v192
	v_pk_mul_f32 v[250:251], v[52:53], v[52:53]
	v_add_f32_e32 v234, v52, v53
	v_add_f32_e32 v235, v250, v251
	v_cndmask_b32_e64 v194, v234, v235, s[4:5]
	v_cndmask_b32_e64 v195, v235, v234, s[4:5]
	ds_bpermute_b32 v194, v236, v194
	v_pk_mul_f32 v[250:251], v[60:61], v[60:61]
	v_add_f32_e32 v234, v60, v61
	v_add_f32_e32 v235, v250, v251
	v_cndmask_b32_e64 v196, v234, v235, s[4:5]
	v_cndmask_b32_e64 v197, v235, v234, s[4:5]
	ds_bpermute_b32 v196, v236, v196
	v_pk_mul_f32 v[250:251], v[58:59], v[58:59]
	v_add_f32_e32 v234, v58, v59
	v_add_f32_e32 v235, v250, v251
	v_cndmask_b32_e64 v198, v234, v235, s[4:5]
	v_cndmask_b32_e64 v199, v235, v234, s[4:5]
	ds_bpermute_b32 v198, v236, v198
	v_pk_mul_f32 v[250:251], v[54:55], v[54:55]
	v_add_f32_e32 v234, v54, v55
	v_add_f32_e32 v235, v250, v251
	v_cndmask_b32_e64 v200, v234, v235, s[4:5]
	v_cndmask_b32_e64 v201, v235, v234, s[4:5]
	ds_bpermute_b32 v200, v236, v200
	v_pk_mul_f32 v[250:251], v[64:65], v[64:65]
	v_add_f32_e32 v234, v64, v65
	v_add_f32_e32 v235, v250, v251
	v_cndmask_b32_e64 v232, v234, v235, s[4:5]
	v_cndmask_b32_e64 v233, v235, v234, s[4:5]
	ds_bpermute_b32 v232, v236, v232
	s_waitcnt lgkmcnt(0)
	v_add_f32_e32 v172, v173, v172
	v_add_f32_e32 v174, v175, v174
	v_add_f32_e32 v176, v177, v176
	v_add_f32_e32 v178, v179, v178
	v_add_f32_e32 v180, v181, v180
	v_add_f32_e32 v182, v183, v182
	v_add_f32_e32 v184, v185, v184
	v_add_f32_e32 v186, v187, v186
	v_add_f32_e32 v188, v189, v188
	v_add_f32_e32 v190, v191, v190
	v_add_f32_e32 v192, v193, v192
	v_add_f32_e32 v194, v195, v194
	v_add_f32_e32 v196, v197, v196
	v_add_f32_e32 v198, v199, v198
	v_add_f32_e32 v200, v201, v200
	v_add_f32_e32 v232, v233, v232
	v_xor_b32_e32 v236, 16, v249
	v_lshlrev_b32_e32 v236, 2, v236
	v_cndmask_b32_e64 v141, v140, v172, s[6:7]
	v_cndmask_b32_e64 v173, v172, v140, s[6:7]
	ds_bpermute_b32 v141, v236, v141
	v_cndmask_b32_e64 v143, v142, v174, s[6:7]
	v_cndmask_b32_e64 v175, v174, v142, s[6:7]
	ds_bpermute_b32 v143, v236, v143
	v_cndmask_b32_e64 v145, v144, v176, s[6:7]
	v_cndmask_b32_e64 v177, v176, v144, s[6:7]
	ds_bpermute_b32 v145, v236, v145
	v_cndmask_b32_e64 v147, v146, v178, s[6:7]
	v_cndmask_b32_e64 v179, v178, v146, s[6:7]
	ds_bpermute_b32 v147, v236, v147
	v_cndmask_b32_e64 v149, v148, v180, s[6:7]
	v_cndmask_b32_e64 v181, v180, v148, s[6:7]
	ds_bpermute_b32 v149, v236, v149
	v_cndmask_b32_e64 v151, v150, v182, s[6:7]
	v_cndmask_b32_e64 v183, v182, v150, s[6:7]
	ds_bpermute_b32 v151, v236, v151
	v_cndmask_b32_e64 v153, v152, v184, s[6:7]
	v_cndmask_b32_e64 v185, v184, v152, s[6:7]
	ds_bpermute_b32 v153, v236, v153
	v_cndmask_b32_e64 v155, v154, v186, s[6:7]
	v_cndmask_b32_e64 v187, v186, v154, s[6:7]
	ds_bpermute_b32 v155, v236, v155
	v_cndmask_b32_e64 v157, v156, v188, s[6:7]
	v_cndmask_b32_e64 v189, v188, v156, s[6:7]
	ds_bpermute_b32 v157, v236, v157
	v_cndmask_b32_e64 v159, v158, v190, s[6:7]
	v_cndmask_b32_e64 v191, v190, v158, s[6:7]
	ds_bpermute_b32 v159, v236, v159
	v_cndmask_b32_e64 v161, v160, v192, s[6:7]
	v_cndmask_b32_e64 v193, v192, v160, s[6:7]
	ds_bpermute_b32 v161, v236, v161
	v_cndmask_b32_e64 v163, v162, v194, s[6:7]
	v_cndmask_b32_e64 v195, v194, v162, s[6:7]
	ds_bpermute_b32 v163, v236, v163
	v_cndmask_b32_e64 v165, v164, v196, s[6:7]
	v_cndmask_b32_e64 v197, v196, v164, s[6:7]
	ds_bpermute_b32 v165, v236, v165
	v_cndmask_b32_e64 v167, v166, v198, s[6:7]
	v_cndmask_b32_e64 v199, v198, v166, s[6:7]
	ds_bpermute_b32 v167, v236, v167
	v_cndmask_b32_e64 v169, v168, v200, s[6:7]
	v_cndmask_b32_e64 v201, v200, v168, s[6:7]
	ds_bpermute_b32 v169, v236, v169
	v_cndmask_b32_e64 v171, v170, v232, s[6:7]
	v_cndmask_b32_e64 v233, v232, v170, s[6:7]
	ds_bpermute_b32 v171, v236, v171
	s_waitcnt lgkmcnt(0)
	v_add_f32_e32 v140, v173, v141
	v_add_f32_e32 v142, v175, v143
	v_add_f32_e32 v144, v177, v145
	v_add_f32_e32 v146, v179, v147
	v_add_f32_e32 v148, v181, v149
	v_add_f32_e32 v150, v183, v151
	v_add_f32_e32 v152, v185, v153
	v_add_f32_e32 v154, v187, v155
	v_add_f32_e32 v156, v189, v157
	v_add_f32_e32 v158, v191, v159
	v_add_f32_e32 v160, v193, v161
	v_add_f32_e32 v162, v195, v163
	v_add_f32_e32 v164, v197, v165
	v_add_f32_e32 v166, v199, v167
	v_add_f32_e32 v168, v201, v169
	v_add_f32_e32 v170, v233, v171
	v_xor_b32_e32 v236, 8, v249
	v_lshlrev_b32_e32 v236, 2, v236
	v_cndmask_b32_e64 v141, v140, v156, s[8:9]
	v_cndmask_b32_e64 v157, v156, v140, s[8:9]
	ds_bpermute_b32 v141, v236, v141
	v_cndmask_b32_e64 v143, v142, v158, s[8:9]
	v_cndmask_b32_e64 v159, v158, v142, s[8:9]
	ds_bpermute_b32 v143, v236, v143
	v_cndmask_b32_e64 v145, v144, v160, s[8:9]
	v_cndmask_b32_e64 v161, v160, v144, s[8:9]
	ds_bpermute_b32 v145, v236, v145
	v_cndmask_b32_e64 v147, v146, v162, s[8:9]
	v_cndmask_b32_e64 v163, v162, v146, s[8:9]
	ds_bpermute_b32 v147, v236, v147
	v_cndmask_b32_e64 v149, v148, v164, s[8:9]
	v_cndmask_b32_e64 v165, v164, v148, s[8:9]
	ds_bpermute_b32 v149, v236, v149
	v_cndmask_b32_e64 v151, v150, v166, s[8:9]
	v_cndmask_b32_e64 v167, v166, v150, s[8:9]
	ds_bpermute_b32 v151, v236, v151
	v_cndmask_b32_e64 v153, v152, v168, s[8:9]
	v_cndmask_b32_e64 v169, v168, v152, s[8:9]
	ds_bpermute_b32 v153, v236, v153
	v_cndmask_b32_e64 v155, v154, v170, s[8:9]
	v_cndmask_b32_e64 v171, v170, v154, s[8:9]
	ds_bpermute_b32 v155, v236, v155
	s_waitcnt lgkmcnt(0)
	v_add_f32_e32 v140, v157, v141
	v_add_f32_e32 v142, v159, v143
	v_add_f32_e32 v144, v161, v145
	v_add_f32_e32 v146, v163, v147
	v_add_f32_e32 v148, v165, v149
	v_add_f32_e32 v150, v167, v151
	v_add_f32_e32 v152, v169, v153
	v_add_f32_e32 v154, v171, v155
	v_xor_b32_e32 v236, 4, v249
	v_lshlrev_b32_e32 v236, 2, v236
	v_cndmask_b32_e64 v141, v140, v148, s[10:11]
	v_cndmask_b32_e64 v149, v148, v140, s[10:11]
	ds_bpermute_b32 v141, v236, v141
	v_cndmask_b32_e64 v143, v142, v150, s[10:11]
	v_cndmask_b32_e64 v151, v150, v142, s[10:11]
	ds_bpermute_b32 v143, v236, v143
	v_cndmask_b32_e64 v145, v144, v152, s[10:11]
	v_cndmask_b32_e64 v153, v152, v144, s[10:11]
	ds_bpermute_b32 v145, v236, v145
	v_cndmask_b32_e64 v147, v146, v154, s[10:11]
	v_cndmask_b32_e64 v155, v154, v146, s[10:11]
	ds_bpermute_b32 v147, v236, v147
	s_waitcnt lgkmcnt(0)
	v_add_f32_e32 v140, v149, v141
	v_add_f32_e32 v142, v151, v143
	v_add_f32_e32 v144, v153, v145
	v_add_f32_e32 v146, v155, v147
	v_xor_b32_e32 v236, 2, v249
	v_lshlrev_b32_e32 v236, 2, v236
	v_cndmask_b32_e64 v141, v140, v144, s[12:13]
	v_cndmask_b32_e64 v145, v144, v140, s[12:13]
	ds_bpermute_b32 v141, v236, v141
	v_cndmask_b32_e64 v143, v142, v146, s[12:13]
	v_cndmask_b32_e64 v147, v146, v142, s[12:13]
	ds_bpermute_b32 v143, v236, v143
	s_waitcnt lgkmcnt(0)
	v_add_f32_e32 v140, v145, v141
	v_add_f32_e32 v142, v147, v143
	v_xor_b32_e32 v236, 1, v249
	v_lshlrev_b32_e32 v236, 2, v236
	v_cndmask_b32_e64 v141, v140, v142, s[14:15]
	v_cndmask_b32_e64 v143, v142, v140, s[14:15]
	ds_bpermute_b32 v141, v236, v141
	s_waitcnt lgkmcnt(0)
	v_add_f32_e32 v140, v143, v141
	ds_write_b32 v67, v140
	s_waitcnt lgkmcnt(0)
	s_barrier
	s_and_saveexec_b64 s[40:41], s[20:21]
	s_cbranch_execz .LBB0_344
	ds_read2_b32 v[140:141], v206 offset1:32
	ds_read2_b32 v[142:143], v206 offset0:64 offset1:96
	ds_read2_b32 v[144:145], v206 offset0:128 offset1:160
	ds_read2_b32 v[146:147], v206 offset0:192 offset1:224
	v_add_u32_e32 v154, 0x400, v206
	s_waitcnt lgkmcnt(3)
	v_mov_b32_e32 v156, v141
	v_mov_b32_e32 v157, v140
	v_pk_add_f32 v[140:141], v[156:157], 0 op_sel_hi:[1,0]
	s_waitcnt lgkmcnt(2)
	v_mov_b32_e32 v156, v143
	v_mov_b32_e32 v157, v142
	ds_read2_b32 v[148:149], v154 offset1:32
	ds_read2_b32 v[150:151], v154 offset0:64 offset1:96
	ds_read2_b32 v[152:153], v154 offset0:128 offset1:160
	ds_read2_b32 v[154:155], v154 offset0:192 offset1:224
	v_pk_add_f32 v[140:141], v[140:141], v[156:157]
	s_waitcnt lgkmcnt(5)
	v_mov_b32_e32 v142, v145
	v_mov_b32_e32 v143, v144
	v_pk_add_f32 v[140:141], v[140:141], v[142:143]
	s_waitcnt lgkmcnt(4)
	v_mov_b32_e32 v142, v147
	v_mov_b32_e32 v143, v146
	v_pk_add_f32 v[140:141], v[140:141], v[142:143]
	s_waitcnt lgkmcnt(3)
	v_mov_b32_e32 v142, v149
	v_mov_b32_e32 v143, v148
	v_pk_add_f32 v[140:141], v[140:141], v[142:143]
	s_waitcnt lgkmcnt(2)
	v_mov_b32_e32 v142, v151
	v_mov_b32_e32 v143, v150
	v_pk_add_f32 v[140:141], v[140:141], v[142:143]
	s_waitcnt lgkmcnt(1)
	v_mov_b32_e32 v142, v153
	v_mov_b32_e32 v143, v152
	v_pk_add_f32 v[140:141], v[140:141], v[142:143]
	s_waitcnt lgkmcnt(0)
	v_mov_b32_e32 v142, v155
	v_mov_b32_e32 v143, v154
	v_pk_add_f32 v[140:141], v[140:141], v[142:143]
	s_nop 0
	v_pk_mul_f32 v[140:141], v[140:141], s[38:39] op_sel_hi:[1,0]
	s_nop 0
	v_fma_f32 v140, -v141, v141, v140
	v_add_f32_e32 v140, 0x358637bd, v140
	v_mul_f32_e32 v142, 0x4f800000, v140
	v_cmp_gt_f32_e32 vcc, s42, v140
	s_nop 1
	v_cndmask_b32_e32 v140, v140, v142, vcc
	v_sqrt_f32_e32 v142, v140
	s_nop 0
	v_add_u32_e32 v143, -1, v142
	v_fma_f32 v144, -v143, v142, v140
	v_cmp_ge_f32_e64 s[22:23], 0, v144
	v_add_u32_e32 v144, 1, v142
	s_nop 0
	v_cndmask_b32_e64 v143, v142, v143, s[22:23]
	v_fma_f32 v142, -v144, v142, v140
	v_cmp_lt_f32_e64 s[22:23], 0, v142
	s_nop 1
	v_cndmask_b32_e64 v142, v143, v144, s[22:23]
	v_mul_f32_e32 v143, 0x37800000, v142
	v_cndmask_b32_e32 v142, v142, v143, vcc
	v_cmp_class_f32_e32 vcc, v140, v248
	s_nop 1
	v_cndmask_b32_e32 v140, v142, v140, vcc
	v_div_scale_f32 v142, s[22:23], v140, v140, 1.0
	v_rcp_f32_e32 v143, v142
	s_nop 0
	v_fma_f32 v144, -v142, v143, 1.0
	v_fmac_f32_e32 v143, v144, v143
	v_div_scale_f32 v144, vcc, 1.0, v140, 1.0
	v_mul_f32_e32 v145, v144, v143
	v_fma_f32 v146, -v142, v145, v144
	v_fmac_f32_e32 v145, v146, v143
	v_fma_f32 v142, -v142, v145, v144
	v_div_fmas_f32 v142, v142, v143, v145
	v_div_fixup_f32 v143, v142, v140, 1.0
	v_add_u32_e32 v140, 0, v66
	v_mov_b32_e32 v142, v141
	v_add_u32_e32 v140, 0x1f800, v140
	ds_write_b64 v140, v[142:143]
	s_branch .LBB0_344
.LBB0_383:
	s_waitcnt vmcnt(0)
	s_mov_b32 s11, 0
	v_cmp_eq_u32_e32 vcc, 0, v0
	s_waitcnt vmcnt(0)
	s_barrier
	s_and_saveexec_b64 s[4:5], vcc
	s_cbranch_execz .LBB0_385
	v_mov_b32_e32 v1, s34
	v_add_co_u32_e32 v2, vcc, 0x6000, v1
	v_mov_b32_e32 v1, s35
	buffer_wbl2 sc1
	v_addc_co_u32_e32 v3, vcc, 0, v1, vcc
	v_mov_b32_e32 v1, 1

.LBB0_396:
	s_cmp_lg_u32 s83, 1
	s_cbranch_scc1 .Lcv_skip
	s_mov_b64 s[98:99], exec
	v_cmp_eq_u32_e64 s[100:101], 0, v0
	s_and_b64 exec, exec, s[100:101]
	s_cbranch_execz .Lcv_rest
	v_mov_b32_e32 v250, 0x6000
	v_mov_b32_e32 v251, 1
	global_atomic_add v250, v251, s[24:25]
.Lcv_rest:
	s_mov_b64 exec, s[98:99]

.LBB0_500:
.LBB0_501:
	s_waitcnt vmcnt(0) lgkmcnt(0)
	s_ashr_i32 s4, s20, 3
	s_mov_b32 s5, 0
	s_cmp_lt_i32 s4, 0
	v_readfirstlane_b32 s23, v0
	s_waitcnt lgkmcnt(0)
	s_barrier
	s_cbranch_scc1 .LBB0_509
	s_lshr_b32 s12, s23, 6
	s_lshr_b32 s13, s23, 8
	s_lshl_b32 s18, s12, 10
	s_lshl_b64 s[14:15], s[4:5], 19
	s_lshl_b32 s16, s22, 19
	s_add_u32 s10, s6, s16
	s_addc_u32 s11, s7, 0
	s_add_u32 s8, s10, 0x2600000
	s_addc_u32 s9, s11, 0
	s_add_i32 s5, s18, 0
	v_lshl_or_b32 v126, v153, 11, v151
	s_add_i32 m0, s5, 0x10000
	v_lshl_or_b32 v122, v150, 11, v151
	global_load_lds_dwordx4 v126, s[8:9]
	s_add_i32 m0, s5, 0x12000
	s_add_u32 s10, s10, 0x2640000
	global_load_lds_dwordx4 v122, s[8:9]
	s_addc_u32 s11, s11, 0
	s_add_i32 m0, s5, 0x14000
	v_lshl_or_b32 v128, v154, 11, v151
	global_load_lds_dwordx4 v126, s[10:11]
	s_add_i32 m0, s5, 0x16000
	s_add_u32 s17, s6, s14
	s_addc_u32 s19, s7, s15
	global_load_lds_dwordx4 v122, s[10:11]
	s_add_u32 s10, s17, 0xd000000
	s_addc_u32 s11, s19, 0
	s_add_i32 s34, s5, 0x2000
	s_mov_b32 m0, s5
	s_add_u32 s20, s17, 0xd040000
	v_lshl_or_b32 v124, v152, 11, v151
	global_load_lds_dwordx4 v128, s[10:11]
	s_mov_b32 m0, s34
	s_addc_u32 s21, s19, 0
	s_add_i32 s35, s5, 0x4000
	global_load_lds_dwordx4 v124, s[10:11]
	s_mov_b32 m0, s35
	s_add_i32 s36, s5, 0x6000
	global_load_lds_dwordx4 v128, s[20:21]
	s_mov_b32 m0, s36
	v_mov_b32_e32 v127, 0
	global_load_lds_dwordx4 v124, s[20:21]
	v_mov_b32_e32 v123, v127
	v_mov_b32_e32 v129, v127
	v_mov_b32_e32 v125, v127
	v_lshl_add_u64 v[8:9], s[8:9], 0, v[126:127]
	v_lshl_add_u64 v[6:7], s[8:9], 0, v[122:123]
	v_lshl_add_u64 v[4:5], s[10:11], 0, v[128:129]
	s_cmp_lg_u32 s13, 1
	v_lshl_add_u64 v[2:3], s[10:11], 0, v[124:125]
	s_cbranch_scc1 .LBB0_504
	s_barrier

.LBB0_620:
	s_mov_b64 s[16:17], 0x80
	s_and_b32 s9, s11, 3
	s_add_i32 m0, s43, 0x18000
	v_lshl_add_u64 v[8:9], v[8:9], 0, s[16:17]
	s_lshl_b32 s5, s36, 13
	s_lshl_b32 s18, s9, 12
	s_waitcnt vmcnt(2)
	s_barrier
	global_load_lds_dwordx4 v[8:9], off
	v_lshl_add_u64 v[6:7], v[6:7], 0, s[16:17]
	s_add_i32 m0, s43, 0x1a000
	s_add_i32 s47, s43, 0x8000
	s_add_i32 s48, s43, 0xa000
	global_load_lds_dwordx4 v[6:7], off
	v_lshl_add_u64 v[4:5], v[4:5], 0, s[16:17]
	s_mov_b32 m0, s47
	s_add_u32 s6, s28, 0x80080
	global_load_lds_dwordx4 v[4:5], off
	v_lshl_add_u64 v[2:3], v[2:3], 0, s[16:17]
	s_mov_b32 m0, s48
	s_addc_u32 s7, s29, 0
	global_load_lds_dwordx4 v[2:3], off
	s_add_i32 m0, s43, 0x1c000
	v_lshl_add_u64 v[2:3], s[6:7], 0, v[132:133]
	global_load_lds_dwordx4 v[2:3], off
	v_lshl_add_u64 v[2:3], s[6:7], 0, v[136:137]
	s_add_i32 m0, s43, 0x1e000
	v_and_b32_e32 v1, 15, v0
	global_load_lds_dwordx4 v[2:3], off
	s_load_dwordx2 s[14:15], s[0:1], 0x0
	s_load_dwordx2 s[6:7], s[0:1], 0xa0
	v_and_b32_e32 v2, 48, v0
	v_lshlrev_b32_e32 v3, 6, v0
	s_movk_i32 s0, 0x3c0
	v_lshlrev_b32_e32 v4, 2, v0
	v_and_or_b32 v3, v3, s0, v2
	v_and_b32_e32 v4, 32, v4
	v_lshl_or_b32 v2, v1, 6, v2
	v_bitop3_b32 v6, v2, s5, v4 bitop3:0xde
	v_lshlrev_b32_e32 v2, 5, v13
	v_bitop3_b32 v151, s18, v3, v4 bitop3:0xf6
	v_and_b32_e32 v2, 0x70000, v2
	v_lshlrev_b32_e32 v4, 12, v12
	v_or3_b32 v2, v10, v2, v4
	s_mov_b64 s[0:1], 0x80080
	v_add_u32_e32 v2, v2, v11
	v_mov_b32_e32 v3, v133
	v_lshl_add_u64 v[138:139], v[2:3], 0, s[0:1]
	v_lshlrev_b32_e32 v2, 9, v0
	v_and_b32_e32 v2, 0x30000, v2
	v_or3_b32 v2, v10, v2, v4
	s_waitcnt vmcnt(6)
	v_add_u32_e32 v2, v2, v11
	v_lshl_add_u64 v[140:141], v[2:3], 0, s[0:1]
	v_add_u32_e32 v152, 0, v6
	s_sext_i32_i8 s10, s4
	v_lshl_or_b32 v204, s36, 6, v1
	s_mov_b32 s49, 0
	v_mov_b64_e32 v[142:143], 0x100
	v_mov_b64_e32 v[144:145], 0xff
	s_add_i32 s50, 0, 0x10000
	s_add_i32 s51, 0, 0x14000
	s_mov_b32 s62, 0x0da24260
	s_mov_b32 s63, 0x7fffffff
	v_max_f32_e64 v254, |v146|, s62
	v_bfi_b32 v146, s63, v254, v146
	v_max_f32_e64 v254, |v147|, s62
	v_bfi_b32 v147, s63, v254, v147
	v_max_f32_e64 v254, |v148|, s62
	v_bfi_b32 v148, s63, v254, v148
	v_max_f32_e64 v254, |v149|, s62
	v_bfi_b32 v149, s63, v254, v149
	v_max_f32_e64 v254, |v242|, s62
	v_bfi_b32 v242, s63, v254, v242
	v_max_f32_e64 v254, |v243|, s62
	v_bfi_b32 v243, s63, v254, v243
	v_max_f32_e64 v254, |v244|, s62
	v_bfi_b32 v244, s63, v254, v244
	v_max_f32_e64 v254, |v245|, s62
	v_bfi_b32 v245, s63, v254, v245
	v_max_f32_e64 v254, |v246|, s62
	v_bfi_b32 v246, s63, v254, v246
	v_max_f32_e64 v254, |v247|, s62
	v_bfi_b32 v247, s63, v254, v247
	v_max_f32_e64 v254, |v248|, s62
	v_bfi_b32 v248, s63, v254, v248
	v_max_f32_e64 v254, |v249|, s62
	v_bfi_b32 v249, s63, v254, v249
	v_max_f32_e64 v254, |v250|, s62
	v_bfi_b32 v250, s63, v254, v250
	v_max_f32_e64 v254, |v251|, s62
	v_bfi_b32 v251, s63, v254, v251
	v_max_f32_e64 v254, |v252|, s62
	v_bfi_b32 v252, s63, v254, v252
	v_max_f32_e64 v254, |v253|, s62
	v_bfi_b32 v253, s63, v254, v253
	v_rcp_f32_e32 v146, v146
	v_rcp_f32_e32 v147, v147
	v_rcp_f32_e32 v148, v148
	v_rcp_f32_e32 v149, v149
	v_rcp_f32_e32 v242, v242
	v_rcp_f32_e32 v243, v243
	v_rcp_f32_e32 v244, v244
	v_rcp_f32_e32 v245, v245
	v_rcp_f32_e32 v246, v246
	v_rcp_f32_e32 v247, v247
	v_rcp_f32_e32 v248, v248
	v_rcp_f32_e32 v249, v249
	v_rcp_f32_e32 v250, v250
	v_rcp_f32_e32 v251, v251
	v_rcp_f32_e32 v252, v252
	v_rcp_f32_e32 v253, v253
	s_nop 0
	v_mul_f32_e32 v124, v124, v244
	v_mul_f32_e32 v125, v125, v245
	v_mul_f32_e32 v128, v128, v148
	v_mul_f32_e32 v129, v129, v149
	v_mul_f32_e32 v126, v126, v146
	v_mul_f32_e32 v127, v127, v147
	v_mul_f32_e32 v122, v122, v242
	v_mul_f32_e32 v123, v123, v243
	v_mul_f32_e32 v120, v120, v248
	v_mul_f32_e32 v121, v121, v249
	v_mul_f32_e32 v118, v118, v246
	v_mul_f32_e32 v119, v119, v247
	v_mul_f32_e32 v116, v116, v252
	v_mul_f32_e32 v117, v117, v253
	v_mul_f32_e32 v114, v114, v250
	v_mul_f32_e32 v115, v115, v251
	v_mul_f32_e32 v112, v112, v148
	v_mul_f32_e32 v113, v113, v149
	v_mul_f32_e32 v110, v110, v146
	v_mul_f32_e32 v111, v111, v147
	v_mul_f32_e32 v108, v108, v244
	v_mul_f32_e32 v109, v109, v245
	v_mul_f32_e32 v106, v106, v242
	v_mul_f32_e32 v107, v107, v243
	v_mul_f32_e32 v104, v104, v248
	v_mul_f32_e32 v105, v105, v249
	v_mul_f32_e32 v102, v102, v246
	v_mul_f32_e32 v103, v103, v247
	v_mul_f32_e32 v100, v100, v252
	v_mul_f32_e32 v101, v101, v253
	v_mul_f32_e32 v98, v98, v250
	v_mul_f32_e32 v99, v99, v251
	v_mul_f32_e32 v96, v96, v148
	v_mul_f32_e32 v97, v97, v149
	v_mul_f32_e32 v94, v94, v146
	v_mul_f32_e32 v95, v95, v147
	v_mul_f32_e32 v92, v92, v244
	v_mul_f32_e32 v93, v93, v245
	v_mul_f32_e32 v90, v90, v242
	v_mul_f32_e32 v91, v91, v243
	v_mul_f32_e32 v88, v88, v248
	v_mul_f32_e32 v89, v89, v249
	v_mul_f32_e32 v86, v86, v246
	v_mul_f32_e32 v87, v87, v247
	v_mul_f32_e32 v80, v156, v252
	v_mul_f32_e32 v81, v157, v253
	v_mul_f32_e32 v78, v154, v250
	v_mul_f32_e32 v79, v155, v251
	v_mul_f32_e32 v84, v84, v148
	v_mul_f32_e32 v85, v85, v149
	v_mul_f32_e32 v82, v82, v146
	v_mul_f32_e32 v83, v83, v147
	v_mul_f32_e32 v76, v160, v244
	v_mul_f32_e32 v77, v161, v245
	v_mul_f32_e32 v74, v158, v242
	v_mul_f32_e32 v75, v159, v243
	v_mul_f32_e32 v72, v164, v248
	v_mul_f32_e32 v73, v165, v249
	v_mul_f32_e32 v70, v162, v246
	v_mul_f32_e32 v71, v163, v247
	v_mul_f32_e32 v68, v168, v252
	v_mul_f32_e32 v69, v169, v253
	v_mul_f32_e32 v66, v166, v250
	v_mul_f32_e32 v67, v167, v251
	v_mul_f32_e32 v64, v172, v148
	v_mul_f32_e32 v65, v173, v149
	v_mul_f32_e32 v62, v170, v146
	v_mul_f32_e32 v63, v171, v147
	v_mul_f32_e32 v60, v176, v244
	v_mul_f32_e32 v61, v177, v245
	v_mul_f32_e32 v58, v174, v242
	v_mul_f32_e32 v59, v175, v243
	v_mul_f32_e32 v56, v180, v248
	v_mul_f32_e32 v57, v181, v249
	v_mul_f32_e32 v54, v178, v246
	v_mul_f32_e32 v55, v179, v247
	v_mul_f32_e32 v52, v184, v252
	v_mul_f32_e32 v53, v185, v253
	v_mul_f32_e32 v50, v182, v250
	v_mul_f32_e32 v51, v183, v251
	v_mul_f32_e32 v48, v188, v148
	v_mul_f32_e32 v49, v189, v149
	v_mul_f32_e32 v46, v186, v146
	v_mul_f32_e32 v47, v187, v147
	v_mul_f32_e32 v44, v192, v244
	v_mul_f32_e32 v45, v193, v245
	v_mul_f32_e32 v42, v190, v242
	v_mul_f32_e32 v43, v191, v243
	v_mul_f32_e32 v40, v196, v248
	v_mul_f32_e32 v41, v197, v249
	v_mul_f32_e32 v38, v194, v246
	v_mul_f32_e32 v39, v195, v247
	v_mul_f32_e32 v36, v200, v252
	v_mul_f32_e32 v37, v201, v253
	v_mul_f32_e32 v34, v198, v250
	v_mul_f32_e32 v35, v199, v251
	v_mul_f32_e32 v32, v208, v148
	v_mul_f32_e32 v33, v209, v149
	v_mul_f32_e32 v30, v206, v146
	v_mul_f32_e32 v31, v207, v147
	v_mul_f32_e32 v28, v212, v244
	v_mul_f32_e32 v29, v213, v245
	v_mul_f32_e32 v26, v210, v242
	v_mul_f32_e32 v27, v211, v243
	v_mul_f32_e32 v24, v216, v248
	v_mul_f32_e32 v25, v217, v249
	v_mul_f32_e32 v22, v214, v246
	v_mul_f32_e32 v23, v215, v247
	v_mul_f32_e32 v16, v220, v252
	v_mul_f32_e32 v17, v221, v253
	v_mul_f32_e32 v14, v218, v250
	v_mul_f32_e32 v15, v219, v251
	v_mul_f32_e32 v20, v224, v148
	v_mul_f32_e32 v21, v225, v149
	v_mul_f32_e32 v18, v222, v146
	v_mul_f32_e32 v19, v223, v147
	v_mul_f32_e32 v12, v228, v244
	v_mul_f32_e32 v13, v229, v245
	v_mul_f32_e32 v10, v226, v242
	v_mul_f32_e32 v11, v227, v243
	v_mul_f32_e32 v8, v232, v248
	v_mul_f32_e32 v9, v233, v249
	v_mul_f32_e32 v6, v230, v246
	v_mul_f32_e32 v7, v231, v247
	v_mul_f32_e32 v4, v236, v252
	v_mul_f32_e32 v5, v237, v253
	v_mul_f32_e32 v2, v234, v250
	v_mul_f32_e32 v3, v235, v251
	global_load_dwordx4 v[230:233], v205, s[92:93]
	global_load_dwordx4 v[234:237], v205, s[92:93] offset:16
	global_load_dwordx4 v[238:241], v205, s[92:93] offset:512
	global_load_dwordx4 v[242:245], v205, s[92:93] offset:528
	s_barrier
	s_branch .LBB0_623

.LBB0_635:
	s_lshl_b32 s0, s9, 5
	s_lshl_b32 s1, s10, 8
	s_or_b32 s0, s1, s0
	v_and_or_b32 v130, v150, 24, s0
	s_ashr_i32 s0, s8, 31
	s_lshr_b32 s0, s0, 28
	s_add_i32 s0, s8, s0
	s_ashr_i32 s0, s0, 4
	s_mul_hi_i32 s1, s0, 0x6000
	s_mulk_i32 s0, 0x6000
	s_add_u32 s0, s24, s0
	v_ashrrev_i32_e32 v131, 31, v130
	s_addc_u32 s1, s25, s1
	v_lshlrev_b64 v[194:195], 2, v[130:131]
	s_lshl_b32 s4, s8, 8
	v_lshl_add_u64 v[130:131], s[0:1], 0, v[194:195]
	s_mov_b32 s2, 0x2904000
	v_add_u32_e32 v196, s4, v204
	v_add_co_u32_e32 v132, vcc, s2, v130
	v_ashrrev_i32_e32 v197, 31, v196
	s_nop 0
	v_addc_co_u32_e32 v133, vcc, 0, v131, vcc
	v_lshl_add_u64 v[202:203], s[14:15], 0, v[194:195]
	v_lshlrev_b64 v[198:199], 13, v[196:197]
	s_barrier
	v_lshl_add_u64 v[132:133], v[202:203], 0, v[198:199]
	s_mov_b64 s[0:1], 0x2904000
	v_lshl_add_u64 v[130:131], v[130:131], 0, s[0:1]
	s_nop 0
	v_or_b32_e32 v146, 16, v196
	v_ashrrev_i32_e32 v147, 31, v146
	v_lshlrev_b64 v[146:147], 13, v[146:147]
	v_lshl_add_u64 v[146:147], v[202:203], 0, v[146:147]
	v_or_b32_e32 v146, 32, v196
	v_ashrrev_i32_e32 v147, 31, v146
	v_lshlrev_b64 v[146:147], 13, v[146:147]
	v_lshl_add_u64 v[146:147], v[202:203], 0, v[146:147]
	v_or_b32_e32 v146, 48, v196
	v_ashrrev_i32_e32 v147, 31, v146
	v_lshlrev_b64 v[146:147], 13, v[146:147]
	v_lshl_add_u64 v[150:151], v[202:203], 0, v[146:147]
	s_nop 0
	v_mbcnt_lo_u32_b32 v200, -1, 0
	v_mbcnt_hi_u32_b32 v200, -1, v200
	v_and_b32_e32 v205, 64, v200
	v_xor_b32_e32 v201, 16, v200
	v_add_u32_e32 v222, 64, v205
	v_cmp_lt_i32_e32 vcc, v201, v222
	v_and_b32_e32 v197, 63, v0
	s_lshl_b32 s0, s9, 2
	v_cndmask_b32_e32 v201, v200, v201, vcc
	v_lshlrev_b32_e32 v205, 2, v201
	v_lshlrev_b32_e32 v1, 4, v1
	s_add_i32 s2, s0, 0
	s_waitcnt vmcnt(0) lgkmcnt(0)
	s_mov_b32 s62, 0x0da24260
	s_mov_b32 s63, 0x7fffffff
	v_mov_b32_e32 v134, v230
	v_mov_b32_e32 v135, v231
	v_mov_b32_e32 v136, v232
	v_mov_b32_e32 v137, v233
	v_mov_b32_e32 v142, v234
	v_mov_b32_e32 v143, v235
	v_mov_b32_e32 v144, v236
	v_mov_b32_e32 v145, v237
	v_mov_b32_e32 v138, v238
	v_mov_b32_e32 v139, v239
	v_mov_b32_e32 v140, v240
	v_mov_b32_e32 v141, v241
	v_mov_b32_e32 v130, v242
	v_mov_b32_e32 v131, v243
	v_mov_b32_e32 v132, v244
	v_mov_b32_e32 v133, v245
	v_max_f32_e64 v254, |v130|, s62
	v_bfi_b32 v130, s63, v254, v130
	v_max_f32_e64 v254, |v131|, s62
	v_bfi_b32 v131, s63, v254, v131
	v_max_f32_e64 v254, |v132|, s62
	v_bfi_b32 v132, s63, v254, v132
	v_max_f32_e64 v254, |v133|, s62
	v_bfi_b32 v133, s63, v254, v133
	v_max_f32_e64 v254, |v134|, s62
	v_bfi_b32 v134, s63, v254, v134
	v_max_f32_e64 v254, |v135|, s62
	v_bfi_b32 v135, s63, v254, v135
	v_max_f32_e64 v254, |v136|, s62
	v_bfi_b32 v136, s63, v254, v136
	v_max_f32_e64 v254, |v137|, s62
	v_bfi_b32 v137, s63, v254, v137
	v_max_f32_e64 v254, |v138|, s62
	v_bfi_b32 v138, s63, v254, v138
	v_max_f32_e64 v254, |v139|, s62
	v_bfi_b32 v139, s63, v254, v139
	v_max_f32_e64 v254, |v140|, s62
	v_bfi_b32 v140, s63, v254, v140
	v_max_f32_e64 v254, |v141|, s62
	v_bfi_b32 v141, s63, v254, v141
	v_max_f32_e64 v254, |v142|, s62
	v_bfi_b32 v142, s63, v254, v142
	v_max_f32_e64 v254, |v143|, s62
	v_bfi_b32 v143, s63, v254, v143
	v_max_f32_e64 v254, |v144|, s62
	v_bfi_b32 v144, s63, v254, v144
	v_max_f32_e64 v254, |v145|, s62
	v_bfi_b32 v145, s63, v254, v145
	s_add_u32 s64, s24, 0x2b04600
	s_addc_u32 s65, s25, 0
	global_load_dwordx4 v[230:233], v194, s[64:65]
	global_load_dwordx4 v[234:237], v194, s[64:65] offset:16
	global_load_dwordx4 v[238:241], v194, s[64:65] offset:512
	global_load_dwordx4 v[242:245], v194, s[64:65] offset:528
	v_pk_mul_f32 v[124:125], v[124:125], v[144:145]
	v_pk_mul_f32 v[128:129], v[128:129], v[136:137]
	v_pk_mul_f32 v[126:127], v[126:127], v[134:135]
	v_pk_mul_f32 v[122:123], v[122:123], v[142:143]
	v_mul_f32_e32 v201, v127, v127
	v_mul_f32_e32 v206, v129, v129
	v_mul_f32_e32 v207, v123, v123
	v_mul_f32_e32 v208, v125, v125
	v_pk_mul_f32 v[120:121], v[120:121], v[140:141]
	v_pk_mul_f32 v[118:119], v[118:119], v[138:139]
	v_fmac_f32_e32 v201, v126, v126
	v_fmac_f32_e32 v206, v128, v128
	v_fmac_f32_e32 v207, v122, v122
	v_fmac_f32_e32 v208, v124, v124
	v_pk_mul_f32 v[116:117], v[116:117], v[132:133]
	v_pk_mul_f32 v[114:115], v[114:115], v[130:131]
	v_mul_f32_e32 v209, v119, v119
	v_mul_f32_e32 v210, v121, v121
	v_add_f32_e32 v201, v201, v206
	v_add_f32_e32 v206, v207, v208
	v_mul_f32_e32 v211, v115, v115
	v_fmac_f32_e32 v209, v118, v118
	v_fmac_f32_e32 v210, v120, v120
	v_add_f32_e32 v201, v201, v206
	v_mul_f32_e32 v206, v117, v117
	v_add_f32_e32 v207, v209, v210
	v_fmac_f32_e32 v211, v114, v114
	v_fmac_f32_e32 v206, v116, v116
	v_add_f32_e32 v201, v201, v207
	v_add_f32_e32 v206, v211, v206
	v_add_f32_e32 v201, v201, v206
	ds_bpermute_b32 v207, v205, v201
	v_xor_b32_e32 v206, 32, v200
	v_cmp_lt_i32_e32 vcc, v206, v222
	s_nop 1
	v_cndmask_b32_e32 v200, v200, v206, vcc
	v_lshlrev_b32_e32 v206, 2, v200
	s_waitcnt lgkmcnt(0)
	v_add_f32_e32 v200, v201, v207
	ds_bpermute_b32 v201, v206, v200
	v_cmp_gt_u32_e32 vcc, 16, v197
	s_and_saveexec_b64 s[0:1], vcc
	s_cbranch_execz .LBB0_637
	s_lshl_b32 s3, s36, 10
	s_add_i32 s3, s2, s3
	v_add_u32_e32 v207, s3, v1
	s_waitcnt lgkmcnt(0)
	v_add_f32_e32 v200, v200, v201
	ds_write_b32 v207, v200

.LBB0_660:
.LBB0_661:
	s_waitcnt vmcnt(0) lgkmcnt(0)
	s_barrier
	s_and_saveexec_b64 s[4:5], s[0:1]
	s_cbranch_execz .LBB0_663
	v_lshlrev_b64 v[0:1], 5, v[0:1]
	v_lshl_add_u64 v[0:1], s[2:3], 0, v[0:1]
	flat_load_dword v2, v[0:1] sc1
	s_waitcnt lgkmcnt(0)
	flat_load_dword v3, v[0:1] offset:4 sc1
	flat_load_dword v5, v[0:1] offset:8 sc1
	flat_load_dword v6, v[0:1] offset:12 sc1
	flat_load_dword v7, v[0:1] offset:16 sc1
	flat_load_dword v8, v[0:1] offset:20 sc1
	flat_load_dword v9, v[0:1] offset:24 sc1
	s_nop 0
	flat_load_dword v0, v[0:1] offset:28 sc1
	v_mov_b32_e32 v1, 0x358637bd
	s_mov_b32 s0, 0xf800000
	s_waitcnt vmcnt(0)
	v_add_f32_e32 v2, 0, v2
	s_waitcnt lgkmcnt(0)
	v_add_f32_e32 v2, v2, v3
	v_add_f32_e32 v2, v2, v5
	v_add_f32_e32 v2, v2, v6
	v_add_f32_e32 v2, v2, v7
	v_add_f32_e32 v2, v2, v8
	v_add_f32_e32 v2, v2, v9
	v_add_f32_e32 v0, v2, v0
	v_fmac_f32_e32 v1, 0x3a000000, v0
	v_mul_f32_e32 v0, 0x4f800000, v1
	v_cmp_gt_f32_e32 vcc, s0, v1
	v_mov_b32_e32 v2, 0x260
	s_nop 0
	v_cndmask_b32_e32 v0, v1, v0, vcc
	v_sqrt_f32_e32 v1, v0
	s_nop 0
	v_add_u32_e32 v3, -1, v1
	v_add_u32_e32 v5, 1, v1
	v_fma_f32 v6, -v3, v1, v0
	v_fma_f32 v7, -v5, v1, v0
	v_cmp_ge_f32_e64 s[0:1], 0, v6
	s_nop 1
	v_cndmask_b32_e64 v1, v1, v3, s[0:1]
	v_cmp_lt_f32_e64 s[0:1], 0, v7
	s_nop 1
	v_cndmask_b32_e64 v1, v1, v5, s[0:1]
	v_mul_f32_e32 v3, 0x37800000, v1
	v_cndmask_b32_e32 v1, v1, v3, vcc
	v_cmp_class_f32_e32 vcc, v0, v2
	s_nop 1
	v_cndmask_b32_e32 v0, v1, v0, vcc
	v_div_scale_f32 v1, s[0:1], v0, v0, 1.0
	v_rcp_f32_e32 v2, v1
	v_div_scale_f32 v3, vcc, 1.0, v0, 1.0
	v_fma_f32 v5, -v1, v2, 1.0
	v_fmac_f32_e32 v2, v5, v2
	v_mul_f32_e32 v5, v3, v2
	v_fma_f32 v6, -v1, v5, v3
	v_fmac_f32_e32 v5, v6, v2
	v_fma_f32 v1, -v1, v5, v3
	v_div_fmas_f32 v1, v1, v2, v5
	v_div_fixup_f32 v0, v1, v0, 1.0
	v_lshl_add_u32 v1, v4, 2, 0
	ds_write_b32 v1, v0 offset:4096
.LBB0_663:
	s_or_b64 exec, exec, s[4:5]
	v_lshl_add_u64 v[0:1], s[24:25], 0, v[194:195]
	s_mov_b64 s[0:1], 0x2b04600
	s_waitcnt lgkmcnt(0)
	v_lshl_add_u64 v[2:3], v[0:1], 0, s[0:1]
	v_add_co_u32_e32 v0, vcc, 0x2b04000, v0
	s_waitcnt lgkmcnt(0)
	s_barrier
	s_nop 0
	v_addc_co_u32_e32 v1, vcc, 0, v1, vcc
	s_nop 0
	s_waitcnt vmcnt(0)
	v_mov_b32_e32 v12, v230
	v_mov_b32_e32 v13, v231
	v_mov_b32_e32 v14, v232
	v_mov_b32_e32 v15, v233
	v_mov_b32_e32 v8, v234
	v_mov_b32_e32 v9, v235
	v_mov_b32_e32 v10, v236
	v_mov_b32_e32 v11, v237
	v_mov_b32_e32 v4, v238
	v_mov_b32_e32 v5, v239
	v_mov_b32_e32 v6, v240
	v_mov_b32_e32 v7, v241
	v_mov_b32_e32 v0, v242
	v_mov_b32_e32 v1, v243
	v_mov_b32_e32 v2, v244
	v_mov_b32_e32 v3, v245
	v_lshl_add_u32 v81, v204, 2, 0
	v_add_u32_e32 v134, 0x1000, v81
	ds_read2_b32 v[86:87], v134 offset1:16
	v_add_u32_e32 v84, 32, v196
	ds_read2_b32 v[108:109], v134 offset0:32 offset1:48
	v_ashrrev_i32_e32 v85, 31, v84
	v_add_u32_e32 v80, 16, v196
	v_lshlrev_b64 v[84:85], 13, v[84:85]
	v_ashrrev_i32_e32 v81, 31, v80
	v_lshl_add_u64 v[84:85], s[6:7], 0, v[84:85]
	v_lshl_add_u64 v[76:77], s[6:7], 0, v[198:199]
	v_lshlrev_b64 v[80:81], 13, v[80:81]
	v_lshl_add_u64 v[110:111], v[84:85], 0, v[194:195]
	s_waitcnt lgkmcnt(0)
	v_pk_mul_f32 v[106:107], v[128:129], v[86:87] op_sel_hi:[1,0]
	v_pk_mul_f32 v[104:105], v[126:127], v[86:87] op_sel_hi:[1,0]
	v_pk_mul_f32 v[84:85], v[122:123], v[86:87] op_sel_hi:[1,0]
	v_pk_mul_f32 v[88:89], v[124:125], v[86:87] op_sel_hi:[1,0]
	v_pk_mul_f32 v[92:93], v[118:119], v[86:87] op_sel_hi:[1,0]
	v_pk_mul_f32 v[90:91], v[120:121], v[86:87] op_sel_hi:[1,0]
	v_pk_mul_f32 v[112:113], v[114:115], v[86:87] op_sel_hi:[1,0]
	v_pk_mul_f32 v[114:115], v[116:117], v[86:87] op_sel_hi:[1,0]
	v_mov_b32_e32 v86, v87
	v_lshl_add_u64 v[76:77], v[76:77], 0, v[194:195]
	v_lshl_add_u64 v[80:81], s[6:7], 0, v[80:81]
	v_pk_mul_f32 v[100:101], v[170:171], v[108:109] op_sel_hi:[1,0]
	v_pk_mul_f32 v[102:103], v[172:173], v[108:109] op_sel_hi:[1,0]
	v_pk_mul_f32 v[124:125], v[192:193], v[86:87] op_sel_hi:[1,0]
	v_pk_mul_f32 v[126:127], v[190:191], v[86:87] op_sel_hi:[1,0]
	v_pk_mul_f32 v[96:97], v[186:187], v[86:87] op_sel_hi:[1,0]
	v_pk_mul_f32 v[94:95], v[188:189], v[86:87] op_sel_hi:[1,0]
	v_pk_mul_f32 v[128:129], v[182:183], v[86:87] op_sel_hi:[1,0]
	v_pk_mul_f32 v[98:99], v[184:185], v[86:87] op_sel_hi:[1,0]
	v_pk_mul_f32 v[130:131], v[178:179], v[86:87] op_sel_hi:[1,0]
	v_pk_mul_f32 v[132:133], v[180:181], v[86:87] op_sel_hi:[1,0]
	v_lshl_add_u64 v[80:81], v[80:81], 0, v[194:195]
	v_pk_mul_f32 v[116:117], v[176:177], v[108:109] op_sel_hi:[1,0]
	v_pk_mul_f32 v[118:119], v[174:175], v[108:109] op_sel_hi:[1,0]
	v_pk_mul_f32 v[120:121], v[200:201], v[108:109] op_sel_hi:[1,0]
	v_pk_mul_f32 v[122:123], v[168:169], v[108:109] op_sel_hi:[1,0]
	s_waitcnt vmcnt(0)
	v_pk_mul_f32 v[86:87], v[10:11], v[88:89]
	v_pk_mul_f32 v[84:85], v[8:9], v[84:85]
	v_pk_mul_f32 v[90:91], v[6:7], v[90:91]
	v_pk_mul_f32 v[88:89], v[4:5], v[92:93]
	v_pk_mul_f32 v[94:95], v[10:11], v[94:95]
	v_pk_mul_f32 v[92:93], v[8:9], v[96:97]
	v_pk_mul_f32 v[98:99], v[6:7], v[98:99]
	v_pk_mul_f32 v[96:97], v[4:5], v[128:129]
	v_pk_mul_f32 v[102:103], v[10:11], v[102:103]
	v_pk_mul_f32 v[100:101], v[8:9], v[100:101]
	global_store_dwordx4 v[76:77], v[84:87], off offset:16
	global_store_dwordx4 v[76:77], v[88:91], off offset:512
	v_pk_mul_f32 v[104:105], v[12:13], v[104:105]
	v_pk_mul_f32 v[86:87], v[2:3], v[114:115]
	v_pk_mul_f32 v[84:85], v[0:1], v[112:113]
	v_pk_mul_f32 v[106:107], v[14:15], v[106:107]
	v_pk_mul_f32 v[88:89], v[12:13], v[126:127]
	v_pk_mul_f32 v[90:91], v[14:15], v[124:125]
	global_store_dwordx4 v[80:81], v[92:95], off offset:16
	global_store_dwordx4 v[80:81], v[96:99], off offset:512
	s_nop 0
	v_pk_mul_f32 v[94:95], v[2:3], v[132:133]
	v_pk_mul_f32 v[92:93], v[0:1], v[130:131]
	v_pk_mul_f32 v[96:97], v[12:13], v[118:119]
	v_pk_mul_f32 v[98:99], v[14:15], v[116:117]
	global_store_dwordx4 v[110:111], v[100:103], off offset:16
	global_store_dwordx4 v[76:77], v[104:107], off
	global_store_dwordx4 v[76:77], v[84:87], off offset:528
	global_store_dwordx4 v[80:81], v[88:91], off
	global_store_dwordx4 v[80:81], v[92:95], off offset:528
	global_store_dwordx4 v[110:111], v[96:99], off
	v_pk_mul_f32 v[86:87], v[6:7], v[122:123]
	v_pk_mul_f32 v[84:85], v[4:5], v[120:121]
	v_pk_mul_f32 v[76:77], v[162:163], v[108:109] op_sel_hi:[1,0]
	global_store_dwordx4 v[110:111], v[84:87], off offset:512
	v_pk_mul_f32 v[80:81], v[164:165], v[108:109] op_sel_hi:[1,0]
	ds_read2_b32 v[88:89], v134 offset0:128 offset1:144
	v_pk_mul_f32 v[84:85], v[0:1], v[76:77]
	v_add_u32_e32 v76, 48, v196
	v_ashrrev_i32_e32 v77, 31, v76
	v_pk_mul_f32 v[86:87], v[2:3], v[80:81]
	v_mov_b32_e32 v80, v109
	v_lshlrev_b64 v[76:77], 13, v[76:77]
	global_store_dwordx4 v[110:111], v[84:87], off offset:528
	v_lshl_add_u64 v[76:77], s[6:7], 0, v[76:77]
	v_lshl_add_u64 v[76:77], v[76:77], 0, v[194:195]
	v_pk_mul_f32 v[84:85], v[158:159], v[80:81] op_sel_hi:[1,0]
	v_pk_mul_f32 v[86:87], v[160:161], v[80:81] op_sel_hi:[1,0]
	v_pk_mul_f32 v[84:85], v[12:13], v[84:85]
	v_pk_mul_f32 v[86:87], v[14:15], v[86:87]
	global_store_dwordx4 v[76:77], v[84:87], off
	s_waitcnt lgkmcnt(0)
	v_pk_mul_f32 v[50:51], v[50:51], v[88:89] op_sel_hi:[1,0]
	v_pk_mul_f32 v[52:53], v[52:53], v[88:89] op_sel_hi:[1,0]
	v_pk_mul_f32 v[84:85], v[154:155], v[80:81] op_sel_hi:[1,0]
	v_pk_mul_f32 v[86:87], v[156:157], v[80:81] op_sel_hi:[1,0]
	v_pk_mul_f32 v[84:85], v[8:9], v[84:85]
	v_pk_mul_f32 v[86:87], v[10:11], v[86:87]
	global_store_dwordx4 v[76:77], v[84:87], off offset:16
	v_pk_mul_f32 v[52:53], v[2:3], v[52:53]
	v_pk_mul_f32 v[50:51], v[0:1], v[50:51]
	v_pk_mul_f32 v[84:85], v[150:151], v[80:81] op_sel_hi:[1,0]
	v_pk_mul_f32 v[86:87], v[152:153], v[80:81] op_sel_hi:[1,0]
	v_pk_mul_f32 v[84:85], v[4:5], v[84:85]
	v_pk_mul_f32 v[86:87], v[6:7], v[86:87]
	global_store_dwordx4 v[76:77], v[84:87], off offset:512
	v_pk_mul_f32 v[62:63], v[62:63], v[88:89] op_sel_hi:[1,0]
	v_pk_mul_f32 v[64:65], v[64:65], v[88:89] op_sel_hi:[1,0]
	v_pk_mul_f32 v[84:85], v[146:147], v[80:81] op_sel_hi:[1,0]
	v_pk_mul_f32 v[80:81], v[148:149], v[80:81] op_sel_hi:[1,0]
	v_pk_mul_f32 v[84:85], v[0:1], v[84:85]
	v_pk_mul_f32 v[86:87], v[2:3], v[80:81]
	global_store_dwordx4 v[76:77], v[84:87], off offset:528
	v_lshl_add_u64 v[76:77], s[6:7], 0, v[166:167]
	v_lshl_add_u64 v[76:77], v[76:77], 0, v[194:195]
	global_store_dwordx4 v[76:77], v[50:53], off offset:528
	v_pk_mul_f32 v[64:65], v[14:15], v[64:65]
	v_pk_mul_f32 v[62:63], v[12:13], v[62:63]
	v_add_u32_e32 v50, 0x90, v196
	v_ashrrev_i32_e32 v51, 31, v50
	v_mov_b32_e32 v52, v89
	v_lshlrev_b64 v[50:51], 13, v[50:51]
	v_lshl_add_u64 v[50:51], s[6:7], 0, v[50:51]
	v_pk_mul_f32 v[38:39], v[38:39], v[52:53] op_sel_hi:[1,0]
	v_pk_mul_f32 v[40:41], v[40:41], v[52:53] op_sel_hi:[1,0]
	v_lshl_add_u64 v[50:51], v[50:51], 0, v[194:195]
	v_pk_mul_f32 v[40:41], v[6:7], v[40:41]
	v_pk_mul_f32 v[38:39], v[4:5], v[38:39]
	global_store_dwordx4 v[50:51], v[38:41], off offset:512
	v_pk_mul_f32 v[34:35], v[34:35], v[52:53] op_sel_hi:[1,0]
	v_pk_mul_f32 v[36:37], v[36:37], v[52:53] op_sel_hi:[1,0]
	ds_read2_b32 v[38:39], v134 offset0:160 offset1:176
	v_pk_mul_f32 v[36:37], v[2:3], v[36:37]
	v_pk_mul_f32 v[34:35], v[0:1], v[34:35]
	global_store_dwordx4 v[50:51], v[34:37], off offset:528
	v_pk_mul_f32 v[46:47], v[46:47], v[52:53] op_sel_hi:[1,0]
	s_waitcnt lgkmcnt(0)
	v_pk_mul_f32 v[22:23], v[22:23], v[38:39] op_sel_hi:[1,0]
	v_add_u32_e32 v34, 0xa0, v196
	v_ashrrev_i32_e32 v35, 31, v34
	v_lshlrev_b64 v[34:35], 13, v[34:35]
	v_lshl_add_u64 v[34:35], s[6:7], 0, v[34:35]
	v_pk_mul_f32 v[24:25], v[24:25], v[38:39] op_sel_hi:[1,0]
	v_lshl_add_u64 v[34:35], v[34:35], 0, v[194:195]
	v_pk_mul_f32 v[24:25], v[6:7], v[24:25]
	v_pk_mul_f32 v[22:23], v[4:5], v[22:23]
	v_pk_mul_f32 v[16:17], v[16:17], v[38:39] op_sel_hi:[1,0]
	global_store_dwordx4 v[34:35], v[22:25], off offset:512
	v_pk_mul_f32 v[48:49], v[48:49], v[52:53] op_sel_hi:[1,0]
	v_pk_mul_f32 v[30:31], v[30:31], v[38:39] op_sel_hi:[1,0]
	v_pk_mul_f32 v[22:23], v[82:83], v[38:39] op_sel_hi:[1,0]
	v_pk_mul_f32 v[24:25], v[2:3], v[16:17]
	v_add_u32_e32 v16, 0xb0, v196
	v_pk_mul_f32 v[22:23], v[0:1], v[22:23]
	v_ashrrev_i32_e32 v17, 31, v16
	global_store_dwordx4 v[34:35], v[22:25], off offset:528
	v_lshlrev_b64 v[16:17], 13, v[16:17]
	v_pk_mul_f32 v[32:33], v[32:33], v[38:39] op_sel_hi:[1,0]
	v_mov_b32_e32 v22, v39
	v_pk_mul_f32 v[24:25], v[78:79], v[22:23] op_sel_hi:[1,0]
	v_pk_mul_f32 v[20:21], v[20:21], v[22:23] op_sel_hi:[1,0]
	v_lshl_add_u64 v[16:17], s[6:7], 0, v[16:17]
	v_pk_mul_f32 v[48:49], v[14:15], v[48:49]
	v_pk_mul_f32 v[46:47], v[12:13], v[46:47]
	v_pk_mul_f32 v[32:33], v[14:15], v[32:33]
	v_pk_mul_f32 v[30:31], v[12:13], v[30:31]
	v_pk_mul_f32 v[14:15], v[14:15], v[20:21]
	v_pk_mul_f32 v[12:13], v[12:13], v[24:25]
	v_lshl_add_u64 v[16:17], v[16:17], 0, v[194:195]
	v_pk_mul_f32 v[58:59], v[58:59], v[88:89] op_sel_hi:[1,0]
	v_pk_mul_f32 v[60:61], v[60:61], v[88:89] op_sel_hi:[1,0]
	v_pk_mul_f32 v[42:43], v[42:43], v[52:53] op_sel_hi:[1,0]
	v_pk_mul_f32 v[44:45], v[44:45], v[52:53] op_sel_hi:[1,0]
	v_pk_mul_f32 v[26:27], v[26:27], v[38:39] op_sel_hi:[1,0]
	v_pk_mul_f32 v[28:29], v[28:29], v[38:39] op_sel_hi:[1,0]
	global_store_dwordx4 v[16:17], v[12:15], off
	v_pk_mul_f32 v[60:61], v[10:11], v[60:61]
	v_pk_mul_f32 v[58:59], v[8:9], v[58:59]
	v_pk_mul_f32 v[12:13], v[74:75], v[22:23] op_sel_hi:[1,0]
	v_pk_mul_f32 v[14:15], v[18:19], v[22:23] op_sel_hi:[1,0]
	v_pk_mul_f32 v[44:45], v[10:11], v[44:45]
	v_pk_mul_f32 v[42:43], v[8:9], v[42:43]
	v_pk_mul_f32 v[28:29], v[10:11], v[28:29]
	v_pk_mul_f32 v[26:27], v[8:9], v[26:27]
	v_pk_mul_f32 v[10:11], v[10:11], v[14:15]
	v_pk_mul_f32 v[8:9], v[8:9], v[12:13]
	v_pk_mul_f32 v[54:55], v[54:55], v[88:89] op_sel_hi:[1,0]
	v_pk_mul_f32 v[56:57], v[56:57], v[88:89] op_sel_hi:[1,0]
	global_store_dwordx4 v[16:17], v[8:11], off offset:16
	v_pk_mul_f32 v[56:57], v[6:7], v[56:57]
	v_pk_mul_f32 v[54:55], v[4:5], v[54:55]
	v_pk_mul_f32 v[8:9], v[70:71], v[22:23] op_sel_hi:[1,0]
	v_pk_mul_f32 v[10:11], v[72:73], v[22:23] op_sel_hi:[1,0]
	v_pk_mul_f32 v[4:5], v[4:5], v[8:9]
	v_pk_mul_f32 v[6:7], v[6:7], v[10:11]
	global_store_dwordx4 v[16:17], v[4:7], off offset:512
	global_store_dwordx4 v[76:77], v[62:65], off
	global_store_dwordx4 v[76:77], v[58:61], off offset:16
	v_pk_mul_f32 v[4:5], v[66:67], v[22:23] op_sel_hi:[1,0]
	v_pk_mul_f32 v[6:7], v[68:69], v[22:23] op_sel_hi:[1,0]
	v_pk_mul_f32 v[0:1], v[0:1], v[4:5]
	v_pk_mul_f32 v[2:3], v[2:3], v[6:7]
	global_store_dwordx4 v[76:77], v[54:57], off offset:512
	global_store_dwordx4 v[50:51], v[46:49], off
	global_store_dwordx4 v[50:51], v[42:45], off offset:16
	global_store_dwordx4 v[34:35], v[30:33], off
	global_store_dwordx4 v[34:35], v[26:29], off offset:16
	global_store_dwordx4 v[16:17], v[0:3], off offset:528
